# outproj tiles: next tile's origin, DMA pointers and first k-stage LDS-DMA issued right after the last k-stage so they land under the epilogue (guide lever 7.10); next header skips its prologue DMA
# baseline (speedup 1.0000x reference)
.LBB0_86:
.LBB0_87:
	v_readlane_b32 s0, v247, 62
	v_readlane_b32 s1, v247, 63
	s_andn2_b64 vcc, exec, s[0:1]
	s_cbranch_vccnz .LBB0_92
	v_readlane_b32 s2, v246, 46
	s_movk_i32 s12, 0x70
	s_mov_b32 s13, 0
.LBB0_89:
	s_ashr_i32 s0, s2, 31
	s_lshr_b32 s0, s0, 26
	s_add_i32 s0, s2, s0
	s_andn2_b32 s0, s0, 63
	s_sub_i32 s1, s2, s0
	s_bfe_i32 s22, s1, 0x80000
	s_bfe_u32 s22, s22, 0x3000c
	s_add_i32 s23, s1, s22
	s_bfe_i32 s22, s23, 0x80000
	s_sext_i32_i16 s22, s22
	s_and_b32 s22, s22, -8
	s_add_i32 s22, s22, s0
	v_readlane_b32 s0, v246, 0
	s_or_b32 s22, s22, s0
	s_and_b32 s0, s23, 0xf8
	s_sub_i32 s0, s1, s0
	s_sext_i32_i8 s0, s0
	s_lshl_b32 s24, s22, 7
	s_lshl_b32 s23, s0, 7
	s_mov_b64 s[0:1], s[8:9]
	v_ashrrev_i32_e32 v1, 1, v184
	v_and_b32_e32 v1, 0xffffffc0, v1
	v_lshrrev_b32_e32 v67, 3, v184
	v_and_b32_e32 v67, 4, v67
	v_add_u32_e32 v1, s24, v1
	v_or_b32_e32 v1, v1, v67
	v_and_b32_e32 v68, 0x5f, v184
	v_or_b32_e32 v68, s23, v68
	v_lshlrev_b32_e32 v69, 2, v68
	v_lshl_add_u32 v70, v1, 12, v69
	s_add_i32 s28, s24, 0xffffe000
	s_ashr_i32 s28, s28, 12
	s_mulk_i32 s28, 0xc00
	s_addk_i32 s28, 0x800
	s_cmp_gt_i32 s22, 63
	s_cselect_b32 s28, s28, 0x6800
	v_add_lshl_u32 v71, v68, s28, 2
	v_mov_b32_e32 v218, v70
	v_add_u32_e32 v219, 0x1000, v70
	v_add_u32_e32 v220, 0x2000, v70
	v_add_u32_e32 v221, 0x3000, v70
	v_add_u32_e32 v222, 0x8000, v70
	v_add_u32_e32 v223, 0x9000, v70
	v_add_u32_e32 v224, 0xa000, v70
	v_add_u32_e32 v225, 0xb000, v70
	v_add_u32_e32 v226, 0x10000, v70
	v_add_u32_e32 v227, 0x11000, v70
	v_add_u32_e32 v228, 0x12000, v70
	v_add_u32_e32 v229, 0x13000, v70
	v_add_u32_e32 v230, 0x18000, v70
	v_add_u32_e32 v231, 0x19000, v70
	v_add_u32_e32 v232, 0x1a000, v70
	v_add_u32_e32 v233, 0x1b000, v70
	global_load_dword v234, v71, s[0:1]
	global_load_dword v235, v71, s[0:1] offset:128
	s_barrier
	v_lshrrev_b32_e32 v122, 6, v184
	v_and_b32_e32 v123, 63, v184
	v_readfirstlane_b32 s39, v122
	s_cmp_eq_u32 s13, 1
	s_cbranch_scc1 .LgT4_p10_skipptr
	v_lshrrev_b32_e32 v124, 4, v123
	v_and_b32_e32 v125, 15, v123
	v_lshlrev_b32_e32 v126, 2, v124
	v_xor_b32_e32 v125, v125, v126
	v_mul_u32_u24_e32 v124, 0x14000, v124
	v_readlane_b32 s0, v247, 58
	v_readlane_b32 s1, v247, 59
	s_nop 3
	s_lshl_b32 s101, s39, 12
	s_mul_i32 s100, s39, 0x140000
	s_lshl_b32 s28, s24, 1
	s_add_u32 s100, s100, s28
	s_add_u32 s100, s100, 0x604a000
	s_add_u32 s28, s68, s100
	s_addc_u32 s29, s69, 0
	v_xor_b32_e32 v126, 0, v125
	v_lshl_add_u32 v126, v126, 4, v124
	v_mov_b32_e32 v127, 0
	v_lshl_add_u64 v[98:99], v[126:127], 0, s[28:29]
	s_add_u32 s28, s28, 0x50000
	s_addc_u32 s29, s29, 0
	v_xor_b32_e32 v126, 1, v125
	v_lshl_add_u32 v126, v126, 4, v124
	v_mov_b32_e32 v127, 0
	v_lshl_add_u64 v[100:101], v[126:127], 0, s[28:29]
	s_add_u32 s28, s28, 0x50000
	s_addc_u32 s29, s29, 0
	v_xor_b32_e32 v126, 2, v125
	v_lshl_add_u32 v126, v126, 4, v124
	v_mov_b32_e32 v127, 0
	v_lshl_add_u64 v[102:103], v[126:127], 0, s[28:29]
	s_add_u32 s28, s28, 0x50000
	s_addc_u32 s29, s29, 0
	v_xor_b32_e32 v126, 3, v125
	v_lshl_add_u32 v126, v126, 4, v124
	v_mov_b32_e32 v127, 0
	v_lshl_add_u64 v[104:105], v[126:127], 0, s[28:29]
	v_lshrrev_b32_e32 v124, 3, v123
	v_lshrrev_b32_e32 v125, 4, v123
	v_and_b32_e32 v126, 7, v123
	s_lshl_b32 s100, s39, 5
	s_add_i32 s100, s100, s23
	s_lshl_b32 s100, s100, 11
	s_add_u32 s0, s0, s100
	s_addc_u32 s1, s1, 0
	v_and_b32_e32 v127, 7, v125
	v_xor_b32_e32 v127, v126, v127
	v_lshlrev_b32_e32 v127, 4, v127
	v_lshl_add_u32 v128, v124, 11, v127
	v_mov_b32_e32 v96, v128
	v_mov_b32_e32 v97, 0
	v_lshl_add_u64 v[106:107], v[96:97], 0, s[0:1]
	s_add_u32 s0, s0, 0x4000
	s_addc_u32 s1, s1, 0
	v_add_u32_e32 v127, 4, v125
	v_and_b32_e32 v127, 7, v127
	v_xor_b32_e32 v127, v126, v127
	v_lshlrev_b32_e32 v127, 4, v127
	v_lshl_add_u32 v128, v124, 11, v127
	v_mov_b32_e32 v96, v128
	v_mov_b32_e32 v97, 0
	v_lshl_add_u64 v[108:109], v[96:97], 0, s[0:1]
	s_add_u32 s0, s0, 0x4000
	s_addc_u32 s1, s1, 0
	v_and_b32_e32 v127, 7, v125
	v_xor_b32_e32 v127, v126, v127
	v_lshlrev_b32_e32 v127, 4, v127
	v_lshl_add_u32 v128, v124, 11, v127
	v_mov_b32_e32 v96, v128
	v_mov_b32_e32 v97, 0
	v_lshl_add_u64 v[110:111], v[96:97], 0, s[0:1]
	s_add_u32 s0, s0, 0x4000
	s_addc_u32 s1, s1, 0
	v_add_u32_e32 v127, 4, v125
	v_and_b32_e32 v127, 7, v127
	v_xor_b32_e32 v127, v126, v127
	v_lshlrev_b32_e32 v127, 4, v127
	v_lshl_add_u32 v128, v124, 11, v127
	v_mov_b32_e32 v96, v128
	v_mov_b32_e32 v97, 0
	v_lshl_add_u64 v[112:113], v[96:97], 0, s[0:1]
	s_mov_b32 s28, 0x500000
	s_mov_b32 s29, 0
	s_mov_b32 s36, 128
	s_mov_b32 s37, 0
	s_add_u32 m0, s101, 0x0
	s_nop 0
	global_load_lds_dwordx4 v[98:99], off
	v_lshl_add_u64 v[98:99], v[98:99], 0, s[28:29]
	s_add_u32 m0, s101, 0x400
	s_nop 0
	global_load_lds_dwordx4 v[100:101], off
	v_lshl_add_u64 v[100:101], v[100:101], 0, s[28:29]
	s_add_u32 m0, s101, 0x800
	s_nop 0
	global_load_lds_dwordx4 v[102:103], off
	v_lshl_add_u64 v[102:103], v[102:103], 0, s[28:29]
	s_add_u32 m0, s101, 0xc00
	s_nop 0
	global_load_lds_dwordx4 v[104:105], off
	v_lshl_add_u64 v[104:105], v[104:105], 0, s[28:29]
	s_add_u32 m0, s101, 0x4000
	s_nop 0
	global_load_lds_dwordx4 v[106:107], off
	v_lshl_add_u64 v[106:107], v[106:107], 0, s[36:37]
	s_add_u32 m0, s101, 0x4400
	s_nop 0
	global_load_lds_dwordx4 v[108:109], off
	v_lshl_add_u64 v[108:109], v[108:109], 0, s[36:37]
	s_add_u32 m0, s101, 0x4800
	s_nop 0
	global_load_lds_dwordx4 v[110:111], off
	v_lshl_add_u64 v[110:111], v[110:111], 0, s[36:37]
	s_add_u32 m0, s101, 0x4c00
	s_nop 0
	global_load_lds_dwordx4 v[112:113], off
	v_lshl_add_u64 v[112:113], v[112:113], 0, s[36:37]
.LgT4_p10_skipptr:
	s_mov_b32 s28, 0x500000
	s_mov_b32 s29, 0
	s_mov_b32 s36, 128
	s_mov_b32 s37, 0
	v_and_b32_e32 v122, 31, v123
	v_lshrrev_b32_e32 v124, 5, v123
	v_bfe_u32 v125, v123, 4, 1
	v_bfe_u32 v126, v123, 2, 2
	v_and_b32_e32 v127, 3, v123
	s_lshr_b32 s38, s39, 1
	s_and_b32 s39, s39, 1
	v_lshlrev_b32_e32 v96, 1, v124
	v_add_u32_e32 v96, 0, v96
	v_and_b32_e32 v96, 3, v96
	v_lshl_or_b32 v96, v126, 2, v96
	v_lshrrev_b32_e32 v97, 1, v127
	v_lshl_or_b32 v97, v125, 1, v97
	v_or_b32_e32 v97, 0, v97
	s_lshl_b32 s0, s38, 3
	v_or_b32_e32 v97, s0, v97
	v_xor_b32_e32 v97, v97, v96
	v_lshlrev_b32_e32 v96, 3, v124
	v_add3_u32 v96, v96, v126, 0
	v_lshlrev_b32_e32 v96, 8, v96
	v_lshl_add_u32 v96, v97, 4, v96
	v_and_b32_e32 v97, 1, v127
	v_lshl_add_u32 v114, v97, 3, v96
	v_lshlrev_b32_e32 v96, 1, v124
	v_add_u32_e32 v96, 1, v96
	v_and_b32_e32 v96, 3, v96
	v_lshl_or_b32 v96, v126, 2, v96
	v_lshrrev_b32_e32 v97, 1, v127
	v_lshl_or_b32 v97, v125, 1, v97
	v_or_b32_e32 v97, 0, v97
	s_lshl_b32 s0, s38, 3
	v_or_b32_e32 v97, s0, v97
	v_xor_b32_e32 v97, v97, v96
	v_lshlrev_b32_e32 v96, 3, v124
	v_add3_u32 v96, v96, v126, 4
	v_lshlrev_b32_e32 v96, 8, v96
	v_lshl_add_u32 v96, v97, 4, v96
	v_and_b32_e32 v97, 1, v127
	v_lshl_add_u32 v115, v97, 3, v96
	v_lshlrev_b32_e32 v96, 1, v124
	v_add_u32_e32 v96, 0, v96
	v_and_b32_e32 v96, 3, v96
	v_lshl_or_b32 v96, v126, 2, v96
	v_lshrrev_b32_e32 v97, 1, v127
	v_lshl_or_b32 v97, v125, 1, v97
	v_or_b32_e32 v97, 4, v97
	s_lshl_b32 s0, s38, 3
	v_or_b32_e32 v97, s0, v97
	v_xor_b32_e32 v97, v97, v96
	v_lshlrev_b32_e32 v96, 3, v124
	v_add3_u32 v96, v96, v126, 0
	v_lshlrev_b32_e32 v96, 8, v96
	v_lshl_add_u32 v96, v97, 4, v96
	v_and_b32_e32 v97, 1, v127
	v_lshl_add_u32 v116, v97, 3, v96
	v_lshlrev_b32_e32 v96, 1, v124
	v_add_u32_e32 v96, 1, v96
	v_and_b32_e32 v96, 3, v96
	v_lshl_or_b32 v96, v126, 2, v96
	v_lshrrev_b32_e32 v97, 1, v127
	v_lshl_or_b32 v97, v125, 1, v97
	v_or_b32_e32 v97, 4, v97
	s_lshl_b32 s0, s38, 3
	v_or_b32_e32 v97, s0, v97
	v_xor_b32_e32 v97, v97, v96
	v_lshlrev_b32_e32 v96, 3, v124
	v_add3_u32 v96, v96, v126, 4
	v_lshlrev_b32_e32 v96, 8, v96
	v_lshl_add_u32 v96, v97, 4, v96
	v_and_b32_e32 v97, 1, v127
	v_lshl_add_u32 v117, v97, 3, v96
	v_bfe_u32 v96, v122, 1, 3
	v_xor_b32_e32 v96, v96, v124
	v_lshlrev_b32_e32 v96, 4, v96
	v_lshl_add_u32 v96, v122, 7, v96
	s_lshl_b32 s0, s39, 13
	v_add_u32_e32 v118, s0, v96
	v_xor_b32_e32 v119, 0x20, v118
	v_xor_b32_e32 v120, 0x40, v118
	v_xor_b32_e32 v121, 0x60, v118
	v_mov_b32_e32 v2, 0
	v_mov_b32_e32 v3, v2
	v_mov_b32_e32 v4, v2
	v_mov_b32_e32 v5, v2
	v_mov_b32_e32 v6, v2
	v_mov_b32_e32 v7, v2
	v_mov_b32_e32 v8, v2
	v_mov_b32_e32 v9, v2
	v_mov_b32_e32 v10, v2
	v_mov_b32_e32 v11, v2
	v_mov_b32_e32 v12, v2
	v_mov_b32_e32 v13, v2
	v_mov_b32_e32 v14, v2
	v_mov_b32_e32 v15, v2
	v_mov_b32_e32 v16, v2
	v_mov_b32_e32 v17, v2
	v_mov_b32_e32 v18, v2
	v_mov_b32_e32 v19, v2
	v_mov_b32_e32 v20, v2
	v_mov_b32_e32 v21, v2
	v_mov_b32_e32 v22, v2
	v_mov_b32_e32 v23, v2
	v_mov_b32_e32 v24, v2
	v_mov_b32_e32 v25, v2
	v_mov_b32_e32 v26, v2
	v_mov_b32_e32 v27, v2
	v_mov_b32_e32 v28, v2
	v_mov_b32_e32 v29, v2
	v_mov_b32_e32 v30, v2
	v_mov_b32_e32 v31, v2
	v_mov_b32_e32 v32, v2
	v_mov_b32_e32 v33, v2
	v_mov_b32_e32 v34, v2
	v_mov_b32_e32 v35, v2
	v_mov_b32_e32 v36, v2
	v_mov_b32_e32 v37, v2
	v_mov_b32_e32 v38, v2
	v_mov_b32_e32 v39, v2
	v_mov_b32_e32 v40, v2
	v_mov_b32_e32 v41, v2
	v_mov_b32_e32 v42, v2
	v_mov_b32_e32 v43, v2
	v_mov_b32_e32 v44, v2
	v_mov_b32_e32 v45, v2
	v_mov_b32_e32 v46, v2
	v_mov_b32_e32 v47, v2
	v_mov_b32_e32 v48, v2
	v_mov_b32_e32 v49, v2
	v_mov_b32_e32 v50, v2
	v_mov_b32_e32 v51, v2
	v_mov_b32_e32 v52, v2
	v_mov_b32_e32 v53, v2
	v_mov_b32_e32 v54, v2
	v_mov_b32_e32 v55, v2
	v_mov_b32_e32 v56, v2
	v_mov_b32_e32 v57, v2
	v_mov_b32_e32 v58, v2
	v_mov_b32_e32 v59, v2
	v_mov_b32_e32 v60, v2
	v_mov_b32_e32 v61, v2
	v_mov_b32_e32 v62, v2
	v_mov_b32_e32 v63, v2
	v_mov_b32_e32 v64, v2
	v_mov_b32_e32 v65, v2
	v_readlane_b32 s0, v248, 2
	v_readlane_b32 s1, v248, 3
	s_nop 3
	s_add_u32 s38, s0, 0x20000
	s_addc_u32 s39, s1, 0
	s_mov_b32 s100, 7
.LgemmT_p10_loop:
	s_waitcnt vmcnt(0)
	s_barrier
	ds_read_b64_tr_b16 v[66:67], v114 offset:0
	ds_read_b64_tr_b16 v[68:69], v115 offset:0
	ds_read_b64_tr_b16 v[70:71], v116 offset:0
	ds_read_b64_tr_b16 v[72:73], v117 offset:0
	ds_read_b128 v[74:77], v118 offset:16384
	ds_read_b128 v[78:81], v118 offset:20480
	ds_read_b64_tr_b16 v[82:83], v114 offset:4096
	ds_read_b64_tr_b16 v[84:85], v115 offset:4096
	ds_read_b64_tr_b16 v[86:87], v116 offset:4096
	ds_read_b64_tr_b16 v[88:89], v117 offset:4096
	ds_read_b128 v[90:93], v119 offset:16384
	ds_read_b128 v[94:97], v119 offset:20480
	s_add_u32 m0, s101, 0x8000
	s_nop 0
	global_load_lds_dwordx4 v[98:99], off
	v_lshl_add_u64 v[98:99], v[98:99], 0, s[28:29]
	s_add_u32 m0, s101, 0x8400
	s_nop 0
	global_load_lds_dwordx4 v[100:101], off
	v_lshl_add_u64 v[100:101], v[100:101], 0, s[28:29]
	s_waitcnt lgkmcnt(6)
	v_mfma_f32_32x32x16_bf16 v[50:65], v[66:69], v[74:77], v[50:65]
	v_mfma_f32_32x32x16_bf16 v[34:49], v[66:69], v[78:81], v[34:49]
	v_mfma_f32_32x32x16_bf16 v[18:33], v[70:73], v[74:77], v[18:33]
	v_mfma_f32_32x32x16_bf16 v[2:17], v[70:73], v[78:81], v[2:17]
	ds_read_b64_tr_b16 v[66:67], v114 offset:8192
	ds_read_b64_tr_b16 v[68:69], v115 offset:8192
	ds_read_b64_tr_b16 v[70:71], v116 offset:8192
	ds_read_b64_tr_b16 v[72:73], v117 offset:8192
	ds_read_b128 v[74:77], v120 offset:16384
	ds_read_b128 v[78:81], v120 offset:20480
	s_add_u32 m0, s101, 0x8800
	s_nop 0
	global_load_lds_dwordx4 v[102:103], off
	v_lshl_add_u64 v[102:103], v[102:103], 0, s[28:29]
	s_add_u32 m0, s101, 0x8c00
	s_nop 0
	global_load_lds_dwordx4 v[104:105], off
	v_lshl_add_u64 v[104:105], v[104:105], 0, s[28:29]
	s_waitcnt lgkmcnt(6)
	v_mfma_f32_32x32x16_bf16 v[50:65], v[82:85], v[90:93], v[50:65]
	v_mfma_f32_32x32x16_bf16 v[34:49], v[82:85], v[94:97], v[34:49]
	v_mfma_f32_32x32x16_bf16 v[18:33], v[86:89], v[90:93], v[18:33]
	v_mfma_f32_32x32x16_bf16 v[2:17], v[86:89], v[94:97], v[2:17]
	ds_read_b64_tr_b16 v[82:83], v114 offset:12288
	ds_read_b64_tr_b16 v[84:85], v115 offset:12288
	ds_read_b64_tr_b16 v[86:87], v116 offset:12288
	ds_read_b64_tr_b16 v[88:89], v117 offset:12288
	ds_read_b128 v[90:93], v121 offset:16384
	ds_read_b128 v[94:97], v121 offset:20480
	s_add_u32 m0, s101, 0xc010
	s_nop 0
	global_load_lds_dwordx4 v[106:107], off
	v_lshl_add_u64 v[106:107], v[106:107], 0, s[36:37]
	s_add_u32 m0, s101, 0xc410
	s_nop 0
	global_load_lds_dwordx4 v[108:109], off
	v_lshl_add_u64 v[108:109], v[108:109], 0, s[36:37]
	s_waitcnt lgkmcnt(6)
	v_mfma_f32_32x32x16_bf16 v[50:65], v[66:69], v[74:77], v[50:65]
	v_mfma_f32_32x32x16_bf16 v[34:49], v[66:69], v[78:81], v[34:49]
	v_mfma_f32_32x32x16_bf16 v[18:33], v[70:73], v[74:77], v[18:33]
	v_mfma_f32_32x32x16_bf16 v[2:17], v[70:73], v[78:81], v[2:17]
	s_add_u32 m0, s101, 0xc810
	s_nop 0
	global_load_lds_dwordx4 v[110:111], off
	v_lshl_add_u64 v[110:111], v[110:111], 0, s[36:37]
	s_add_u32 m0, s101, 0xcc10
	s_nop 0
	global_load_lds_dwordx4 v[112:113], off
	v_lshl_add_u64 v[112:113], v[112:113], 0, s[36:37]
	s_waitcnt lgkmcnt(0)
	v_mfma_f32_32x32x16_bf16 v[50:65], v[82:85], v[90:93], v[50:65]
	v_mfma_f32_32x32x16_bf16 v[34:49], v[82:85], v[94:97], v[34:49]
	v_mfma_f32_32x32x16_bf16 v[18:33], v[86:89], v[90:93], v[18:33]
	v_mfma_f32_32x32x16_bf16 v[2:17], v[86:89], v[94:97], v[2:17]
	s_waitcnt vmcnt(0)
	s_barrier
	ds_read_b64_tr_b16 v[66:67], v114 offset:32768
	ds_read_b64_tr_b16 v[68:69], v115 offset:32768
	ds_read_b64_tr_b16 v[70:71], v116 offset:32768
	ds_read_b64_tr_b16 v[72:73], v117 offset:32768
	ds_read_b128 v[74:77], v118 offset:49168
	ds_read_b128 v[78:81], v118 offset:53264
	ds_read_b64_tr_b16 v[82:83], v114 offset:36864
	ds_read_b64_tr_b16 v[84:85], v115 offset:36864
	ds_read_b64_tr_b16 v[86:87], v116 offset:36864
	ds_read_b64_tr_b16 v[88:89], v117 offset:36864
	ds_read_b128 v[90:93], v119 offset:49168
	ds_read_b128 v[94:97], v119 offset:53264
	s_add_u32 m0, s101, 0x0
	s_nop 0
	global_load_lds_dwordx4 v[98:99], off
	v_lshl_add_u64 v[98:99], v[98:99], 0, s[28:29]
	s_add_u32 m0, s101, 0x400
	s_nop 0
	global_load_lds_dwordx4 v[100:101], off
	v_lshl_add_u64 v[100:101], v[100:101], 0, s[28:29]
	s_waitcnt lgkmcnt(6)
	v_mfma_f32_32x32x16_bf16 v[50:65], v[66:69], v[74:77], v[50:65]
	v_mfma_f32_32x32x16_bf16 v[34:49], v[66:69], v[78:81], v[34:49]
	v_mfma_f32_32x32x16_bf16 v[18:33], v[70:73], v[74:77], v[18:33]
	v_mfma_f32_32x32x16_bf16 v[2:17], v[70:73], v[78:81], v[2:17]
	ds_read_b64_tr_b16 v[66:67], v114 offset:40960
	ds_read_b64_tr_b16 v[68:69], v115 offset:40960
	ds_read_b64_tr_b16 v[70:71], v116 offset:40960
	ds_read_b64_tr_b16 v[72:73], v117 offset:40960
	ds_read_b128 v[74:77], v120 offset:49168
	ds_read_b128 v[78:81], v120 offset:53264
	s_add_u32 m0, s101, 0x800
	s_nop 0
	global_load_lds_dwordx4 v[102:103], off
	v_lshl_add_u64 v[102:103], v[102:103], 0, s[28:29]
	s_add_u32 m0, s101, 0xc00
	s_nop 0
	global_load_lds_dwordx4 v[104:105], off
	v_lshl_add_u64 v[104:105], v[104:105], 0, s[28:29]
	s_waitcnt lgkmcnt(6)
	v_mfma_f32_32x32x16_bf16 v[50:65], v[82:85], v[90:93], v[50:65]
	v_mfma_f32_32x32x16_bf16 v[34:49], v[82:85], v[94:97], v[34:49]
	v_mfma_f32_32x32x16_bf16 v[18:33], v[86:89], v[90:93], v[18:33]
	v_mfma_f32_32x32x16_bf16 v[2:17], v[86:89], v[94:97], v[2:17]
	ds_read_b64_tr_b16 v[82:83], v114 offset:45056
	ds_read_b64_tr_b16 v[84:85], v115 offset:45056
	ds_read_b64_tr_b16 v[86:87], v116 offset:45056
	ds_read_b64_tr_b16 v[88:89], v117 offset:45056
	ds_read_b128 v[90:93], v121 offset:49168
	ds_read_b128 v[94:97], v121 offset:53264
	s_add_u32 m0, s101, 0x4000
	s_nop 0
	global_load_lds_dwordx4 v[106:107], off
	v_lshl_add_u64 v[106:107], v[106:107], 0, s[36:37]
	s_add_u32 m0, s101, 0x4400
	s_nop 0
	global_load_lds_dwordx4 v[108:109], off
	v_lshl_add_u64 v[108:109], v[108:109], 0, s[36:37]
	s_waitcnt lgkmcnt(6)
	v_mfma_f32_32x32x16_bf16 v[50:65], v[66:69], v[74:77], v[50:65]
	v_mfma_f32_32x32x16_bf16 v[34:49], v[66:69], v[78:81], v[34:49]
	v_mfma_f32_32x32x16_bf16 v[18:33], v[70:73], v[74:77], v[18:33]
	v_mfma_f32_32x32x16_bf16 v[2:17], v[70:73], v[78:81], v[2:17]
	s_add_u32 m0, s101, 0x4800
	s_nop 0
	global_load_lds_dwordx4 v[110:111], off
	v_lshl_add_u64 v[110:111], v[110:111], 0, s[36:37]
	s_add_u32 m0, s101, 0x4c00
	s_nop 0
	global_load_lds_dwordx4 v[112:113], off
	v_lshl_add_u64 v[112:113], v[112:113], 0, s[36:37]
	s_waitcnt lgkmcnt(0)
	v_mfma_f32_32x32x16_bf16 v[50:65], v[82:85], v[90:93], v[50:65]
	v_mfma_f32_32x32x16_bf16 v[34:49], v[82:85], v[94:97], v[34:49]
	v_mfma_f32_32x32x16_bf16 v[18:33], v[86:89], v[90:93], v[18:33]
	v_mfma_f32_32x32x16_bf16 v[2:17], v[86:89], v[94:97], v[2:17]
	s_sub_u32 s100, s100, 1
	s_cmp_lg_u32 s100, 0
	s_cbranch_scc1 .LgemmT_p10_loop
	s_waitcnt vmcnt(0)
	s_barrier
	ds_read_b64_tr_b16 v[66:67], v114 offset:0
	ds_read_b64_tr_b16 v[68:69], v115 offset:0
	ds_read_b64_tr_b16 v[70:71], v116 offset:0
	ds_read_b64_tr_b16 v[72:73], v117 offset:0
	ds_read_b128 v[74:77], v118 offset:16384
	ds_read_b128 v[78:81], v118 offset:20480
	ds_read_b64_tr_b16 v[82:83], v114 offset:4096
	ds_read_b64_tr_b16 v[84:85], v115 offset:4096
	ds_read_b64_tr_b16 v[86:87], v116 offset:4096
	ds_read_b64_tr_b16 v[88:89], v117 offset:4096
	ds_read_b128 v[90:93], v119 offset:16384
	ds_read_b128 v[94:97], v119 offset:20480
	s_add_u32 m0, s101, 0x8000
	s_nop 0
	global_load_lds_dwordx4 v[98:99], off
	v_lshl_add_u64 v[98:99], v[98:99], 0, s[28:29]
	s_add_u32 m0, s101, 0x8400
	s_nop 0
	global_load_lds_dwordx4 v[100:101], off
	v_lshl_add_u64 v[100:101], v[100:101], 0, s[28:29]
	s_waitcnt lgkmcnt(6)
	v_mfma_f32_32x32x16_bf16 v[50:65], v[66:69], v[74:77], v[50:65]
	v_mfma_f32_32x32x16_bf16 v[34:49], v[66:69], v[78:81], v[34:49]
	v_mfma_f32_32x32x16_bf16 v[18:33], v[70:73], v[74:77], v[18:33]
	v_mfma_f32_32x32x16_bf16 v[2:17], v[70:73], v[78:81], v[2:17]
	ds_read_b64_tr_b16 v[66:67], v114 offset:8192
	ds_read_b64_tr_b16 v[68:69], v115 offset:8192
	ds_read_b64_tr_b16 v[70:71], v116 offset:8192
	ds_read_b64_tr_b16 v[72:73], v117 offset:8192
	ds_read_b128 v[74:77], v120 offset:16384
	ds_read_b128 v[78:81], v120 offset:20480
	s_add_u32 m0, s101, 0x8800
	s_nop 0
	global_load_lds_dwordx4 v[102:103], off
	v_lshl_add_u64 v[102:103], v[102:103], 0, s[28:29]
	s_add_u32 m0, s101, 0x8c00
	s_nop 0
	global_load_lds_dwordx4 v[104:105], off
	v_lshl_add_u64 v[104:105], v[104:105], 0, s[28:29]
	s_waitcnt lgkmcnt(6)
	v_mfma_f32_32x32x16_bf16 v[50:65], v[82:85], v[90:93], v[50:65]
	v_mfma_f32_32x32x16_bf16 v[34:49], v[82:85], v[94:97], v[34:49]
	v_mfma_f32_32x32x16_bf16 v[18:33], v[86:89], v[90:93], v[18:33]
	v_mfma_f32_32x32x16_bf16 v[2:17], v[86:89], v[94:97], v[2:17]
	ds_read_b64_tr_b16 v[82:83], v114 offset:12288
	ds_read_b64_tr_b16 v[84:85], v115 offset:12288
	ds_read_b64_tr_b16 v[86:87], v116 offset:12288
	ds_read_b64_tr_b16 v[88:89], v117 offset:12288
	ds_read_b128 v[90:93], v121 offset:16384
	ds_read_b128 v[94:97], v121 offset:20480
	s_add_u32 m0, s101, 0xc010
	s_nop 0
	global_load_lds_dwordx4 v[106:107], off
	v_lshl_add_u64 v[106:107], v[106:107], 0, s[36:37]
	s_add_u32 m0, s101, 0xc410
	s_nop 0
	global_load_lds_dwordx4 v[108:109], off
	v_lshl_add_u64 v[108:109], v[108:109], 0, s[36:37]
	s_waitcnt lgkmcnt(6)
	v_mfma_f32_32x32x16_bf16 v[50:65], v[66:69], v[74:77], v[50:65]
	v_mfma_f32_32x32x16_bf16 v[34:49], v[66:69], v[78:81], v[34:49]
	v_mfma_f32_32x32x16_bf16 v[18:33], v[70:73], v[74:77], v[18:33]
	v_mfma_f32_32x32x16_bf16 v[2:17], v[70:73], v[78:81], v[2:17]
	s_add_u32 m0, s101, 0xc810
	s_nop 0
	global_load_lds_dwordx4 v[110:111], off
	v_lshl_add_u64 v[110:111], v[110:111], 0, s[36:37]
	s_add_u32 m0, s101, 0xcc10
	s_nop 0
	global_load_lds_dwordx4 v[112:113], off
	v_lshl_add_u64 v[112:113], v[112:113], 0, s[36:37]
	s_waitcnt lgkmcnt(0)
	v_mfma_f32_32x32x16_bf16 v[50:65], v[82:85], v[90:93], v[50:65]
	v_mfma_f32_32x32x16_bf16 v[34:49], v[82:85], v[94:97], v[34:49]
	v_mfma_f32_32x32x16_bf16 v[18:33], v[86:89], v[90:93], v[18:33]
	v_mfma_f32_32x32x16_bf16 v[2:17], v[86:89], v[94:97], v[2:17]
	s_waitcnt vmcnt(0)
	s_barrier
	ds_read_b64_tr_b16 v[66:67], v114 offset:32768
	ds_read_b64_tr_b16 v[68:69], v115 offset:32768
	ds_read_b64_tr_b16 v[70:71], v116 offset:32768
	ds_read_b64_tr_b16 v[72:73], v117 offset:32768
	ds_read_b128 v[74:77], v118 offset:49168
	ds_read_b128 v[78:81], v118 offset:53264
	ds_read_b64_tr_b16 v[82:83], v114 offset:36864
	ds_read_b64_tr_b16 v[84:85], v115 offset:36864
	ds_read_b64_tr_b16 v[86:87], v116 offset:36864
	ds_read_b64_tr_b16 v[88:89], v117 offset:36864
	ds_read_b128 v[90:93], v119 offset:49168
	ds_read_b128 v[94:97], v119 offset:53264
	global_load_dword v129, v218, s[0:1] nt
	global_load_dword v130, v219, s[0:1] nt
	global_load_dword v131, v220, s[0:1] nt
	global_load_dword v132, v221, s[0:1] nt
	global_load_dword v133, v222, s[0:1] nt
	global_load_dword v134, v223, s[0:1] nt
	global_load_dword v135, v224, s[0:1] nt
	global_load_dword v136, v225, s[0:1] nt
	global_load_dword v137, v226, s[0:1] nt
	global_load_dword v138, v227, s[0:1] nt
	global_load_dword v139, v228, s[0:1] nt
	global_load_dword v140, v229, s[0:1] nt
	global_load_dword v141, v230, s[0:1] nt
	global_load_dword v142, v231, s[0:1] nt
	global_load_dword v143, v232, s[0:1] nt
	global_load_dword v144, v233, s[0:1] nt
	s_waitcnt lgkmcnt(6)
	v_mfma_f32_32x32x16_bf16 v[50:65], v[66:69], v[74:77], v[50:65]
	v_mfma_f32_32x32x16_bf16 v[34:49], v[66:69], v[78:81], v[34:49]
	v_mfma_f32_32x32x16_bf16 v[18:33], v[70:73], v[74:77], v[18:33]
	v_mfma_f32_32x32x16_bf16 v[2:17], v[70:73], v[78:81], v[2:17]
	ds_read_b64_tr_b16 v[66:67], v114 offset:40960
	ds_read_b64_tr_b16 v[68:69], v115 offset:40960
	ds_read_b64_tr_b16 v[70:71], v116 offset:40960
	ds_read_b64_tr_b16 v[72:73], v117 offset:40960
	ds_read_b128 v[74:77], v120 offset:49168
	ds_read_b128 v[78:81], v120 offset:53264
	global_load_dword v145, v218, s[0:1] offset:128 nt
	global_load_dword v146, v219, s[0:1] offset:128 nt
	global_load_dword v147, v220, s[0:1] offset:128 nt
	global_load_dword v148, v221, s[0:1] offset:128 nt
	global_load_dword v149, v222, s[0:1] offset:128 nt
	global_load_dword v150, v223, s[0:1] offset:128 nt
	global_load_dword v151, v224, s[0:1] offset:128 nt
	global_load_dword v152, v225, s[0:1] offset:128 nt
	global_load_dword v153, v226, s[0:1] offset:128 nt
	global_load_dword v154, v227, s[0:1] offset:128 nt
	global_load_dword v155, v228, s[0:1] offset:128 nt
	global_load_dword v156, v229, s[0:1] offset:128 nt
	global_load_dword v157, v230, s[0:1] offset:128 nt
	global_load_dword v158, v231, s[0:1] offset:128 nt
	global_load_dword v159, v232, s[0:1] offset:128 nt
	global_load_dword v160, v233, s[0:1] offset:128 nt
	s_waitcnt lgkmcnt(6)
	v_mfma_f32_32x32x16_bf16 v[50:65], v[82:85], v[90:93], v[50:65]
	v_mfma_f32_32x32x16_bf16 v[34:49], v[82:85], v[94:97], v[34:49]
	v_mfma_f32_32x32x16_bf16 v[18:33], v[86:89], v[90:93], v[18:33]
	v_mfma_f32_32x32x16_bf16 v[2:17], v[86:89], v[94:97], v[2:17]
	ds_read_b64_tr_b16 v[82:83], v114 offset:45056
	ds_read_b64_tr_b16 v[84:85], v115 offset:45056
	ds_read_b64_tr_b16 v[86:87], v116 offset:45056
	ds_read_b64_tr_b16 v[88:89], v117 offset:45056
	ds_read_b128 v[90:93], v121 offset:49168
	ds_read_b128 v[94:97], v121 offset:53264
	global_load_dword v161, v218, s[38:39] nt
	global_load_dword v162, v219, s[38:39] nt
	global_load_dword v163, v220, s[38:39] nt
	global_load_dword v164, v221, s[38:39] nt
	global_load_dword v165, v222, s[38:39] nt
	global_load_dword v166, v223, s[38:39] nt
	global_load_dword v167, v224, s[38:39] nt
	global_load_dword v168, v225, s[38:39] nt
	global_load_dword v169, v226, s[38:39] nt
	global_load_dword v170, v227, s[38:39] nt
	global_load_dword v171, v228, s[38:39] nt
	global_load_dword v172, v229, s[38:39] nt
	global_load_dword v173, v230, s[38:39] nt
	global_load_dword v174, v231, s[38:39] nt
	global_load_dword v175, v232, s[38:39] nt
	global_load_dword v176, v233, s[38:39] nt
	s_waitcnt lgkmcnt(6)
	v_mfma_f32_32x32x16_bf16 v[50:65], v[66:69], v[74:77], v[50:65]
	v_mfma_f32_32x32x16_bf16 v[34:49], v[66:69], v[78:81], v[34:49]
	v_mfma_f32_32x32x16_bf16 v[18:33], v[70:73], v[74:77], v[18:33]
	v_mfma_f32_32x32x16_bf16 v[2:17], v[70:73], v[78:81], v[2:17]
	global_load_dword v177, v218, s[38:39] offset:128 nt
	global_load_dword v202, v219, s[38:39] offset:128 nt
	global_load_dword v203, v220, s[38:39] offset:128 nt
	global_load_dword v204, v221, s[38:39] offset:128 nt
	global_load_dword v205, v222, s[38:39] offset:128 nt
	global_load_dword v206, v223, s[38:39] offset:128 nt
	global_load_dword v207, v224, s[38:39] offset:128 nt
	global_load_dword v208, v225, s[38:39] offset:128 nt
	global_load_dword v209, v226, s[38:39] offset:128 nt
	global_load_dword v210, v227, s[38:39] offset:128 nt
	global_load_dword v211, v228, s[38:39] offset:128 nt
	global_load_dword v212, v229, s[38:39] offset:128 nt
	global_load_dword v213, v230, s[38:39] offset:128 nt
	global_load_dword v214, v231, s[38:39] offset:128 nt
	global_load_dword v215, v232, s[38:39] offset:128 nt
	global_load_dword v216, v233, s[38:39] offset:128 nt
	s_waitcnt lgkmcnt(0)
	v_mfma_f32_32x32x16_bf16 v[50:65], v[82:85], v[90:93], v[50:65]
	v_mfma_f32_32x32x16_bf16 v[34:49], v[82:85], v[94:97], v[34:49]
	v_mfma_f32_32x32x16_bf16 v[18:33], v[86:89], v[90:93], v[18:33]
	v_mfma_f32_32x32x16_bf16 v[2:17], v[86:89], v[94:97], v[2:17]
	v_readlane_b32 s0, v246, 1
	s_nop 1
	s_add_i32 s2, s2, s0
	s_mov_b32 s13, 0
	s_cmpk_gt_i32 s2, 0x13f
	s_cbranch_scc1 .LgT4_p10_nopf
	s_ashr_i32 s0, s2, 31
	s_lshr_b32 s0, s0, 26
	s_add_i32 s0, s2, s0
	s_andn2_b32 s0, s0, 63
	s_sub_i32 s1, s2, s0
	s_bfe_i32 s22, s1, 0x80000
	s_bfe_u32 s22, s22, 0x3000c
	s_add_i32 s23, s1, s22
	s_bfe_i32 s22, s23, 0x80000
	s_sext_i32_i16 s22, s22
	s_and_b32 s22, s22, -8
	s_add_i32 s22, s22, s0
	v_readlane_b32 s0, v246, 0
	s_or_b32 s22, s22, s0
	s_and_b32 s0, s23, 0xf8
	s_sub_i32 s0, s1, s0
	s_sext_i32_i8 s0, s0
	s_lshl_b32 s24, s22, 7
	s_lshl_b32 s23, s0, 7
	v_lshrrev_b32_e32 v122, 6, v184
	v_and_b32_e32 v123, 63, v184
	v_readfirstlane_b32 s39, v122
	v_lshrrev_b32_e32 v124, 4, v123
	v_and_b32_e32 v125, 15, v123
	v_lshlrev_b32_e32 v126, 2, v124
	v_xor_b32_e32 v125, v125, v126
	v_mul_u32_u24_e32 v124, 0x14000, v124
	v_readlane_b32 s0, v247, 58
	v_readlane_b32 s1, v247, 59
	s_nop 3
	s_lshl_b32 s101, s39, 12
	s_mul_i32 s100, s39, 0x140000
	s_lshl_b32 s28, s24, 1
	s_add_u32 s100, s100, s28
	s_add_u32 s100, s100, 0x604a000
	s_add_u32 s28, s68, s100
	s_addc_u32 s29, s69, 0
	v_xor_b32_e32 v126, 0, v125
	v_lshl_add_u32 v126, v126, 4, v124
	v_mov_b32_e32 v127, 0
	v_lshl_add_u64 v[98:99], v[126:127], 0, s[28:29]
	s_add_u32 s28, s28, 0x50000
	s_addc_u32 s29, s29, 0
	v_xor_b32_e32 v126, 1, v125
	v_lshl_add_u32 v126, v126, 4, v124
	v_mov_b32_e32 v127, 0
	v_lshl_add_u64 v[100:101], v[126:127], 0, s[28:29]
	s_add_u32 s28, s28, 0x50000
	s_addc_u32 s29, s29, 0
	v_xor_b32_e32 v126, 2, v125
	v_lshl_add_u32 v126, v126, 4, v124
	v_mov_b32_e32 v127, 0
	v_lshl_add_u64 v[102:103], v[126:127], 0, s[28:29]
	s_add_u32 s28, s28, 0x50000
	s_addc_u32 s29, s29, 0
	v_xor_b32_e32 v126, 3, v125
	v_lshl_add_u32 v126, v126, 4, v124
	v_mov_b32_e32 v127, 0
	v_lshl_add_u64 v[104:105], v[126:127], 0, s[28:29]
	v_lshrrev_b32_e32 v124, 3, v123
	v_lshrrev_b32_e32 v125, 4, v123
	v_and_b32_e32 v126, 7, v123
	s_lshl_b32 s100, s39, 5
	s_add_i32 s100, s100, s23
	s_lshl_b32 s100, s100, 11
	s_add_u32 s0, s0, s100
	s_addc_u32 s1, s1, 0
	v_and_b32_e32 v127, 7, v125
	v_xor_b32_e32 v127, v126, v127
	v_lshlrev_b32_e32 v127, 4, v127
	v_lshl_add_u32 v128, v124, 11, v127
	v_mov_b32_e32 v96, v128
	v_mov_b32_e32 v97, 0
	v_lshl_add_u64 v[106:107], v[96:97], 0, s[0:1]
	s_add_u32 s0, s0, 0x4000
	s_addc_u32 s1, s1, 0
	v_add_u32_e32 v127, 4, v125
	v_and_b32_e32 v127, 7, v127
	v_xor_b32_e32 v127, v126, v127
	v_lshlrev_b32_e32 v127, 4, v127
	v_lshl_add_u32 v128, v124, 11, v127
	v_mov_b32_e32 v96, v128
	v_mov_b32_e32 v97, 0
	v_lshl_add_u64 v[108:109], v[96:97], 0, s[0:1]
	s_add_u32 s0, s0, 0x4000
	s_addc_u32 s1, s1, 0
	v_and_b32_e32 v127, 7, v125
	v_xor_b32_e32 v127, v126, v127
	v_lshlrev_b32_e32 v127, 4, v127
	v_lshl_add_u32 v128, v124, 11, v127
	v_mov_b32_e32 v96, v128
	v_mov_b32_e32 v97, 0
	v_lshl_add_u64 v[110:111], v[96:97], 0, s[0:1]
	s_add_u32 s0, s0, 0x4000
	s_addc_u32 s1, s1, 0
	v_add_u32_e32 v127, 4, v125
	v_and_b32_e32 v127, 7, v127
	v_xor_b32_e32 v127, v126, v127
	v_lshlrev_b32_e32 v127, 4, v127
	v_lshl_add_u32 v128, v124, 11, v127
	v_mov_b32_e32 v96, v128
	v_mov_b32_e32 v97, 0
	v_lshl_add_u64 v[112:113], v[96:97], 0, s[0:1]
	s_mov_b32 s28, 0x500000
	s_mov_b32 s29, 0
	s_mov_b32 s36, 128
	s_mov_b32 s37, 0
	s_add_u32 m0, s101, 0x0
	s_nop 0
	global_load_lds_dwordx4 v[98:99], off
	v_lshl_add_u64 v[98:99], v[98:99], 0, s[28:29]
	s_add_u32 m0, s101, 0x400
	s_nop 0
	global_load_lds_dwordx4 v[100:101], off
	v_lshl_add_u64 v[100:101], v[100:101], 0, s[28:29]
	s_add_u32 m0, s101, 0x800
	s_nop 0
	global_load_lds_dwordx4 v[102:103], off
	v_lshl_add_u64 v[102:103], v[102:103], 0, s[28:29]
	s_add_u32 m0, s101, 0xc00
	s_nop 0
	global_load_lds_dwordx4 v[104:105], off
	v_lshl_add_u64 v[104:105], v[104:105], 0, s[28:29]
	s_add_u32 m0, s101, 0x4000
	s_nop 0
	global_load_lds_dwordx4 v[106:107], off
	v_lshl_add_u64 v[106:107], v[106:107], 0, s[36:37]
	s_add_u32 m0, s101, 0x4400
	s_nop 0
	global_load_lds_dwordx4 v[108:109], off
	v_lshl_add_u64 v[108:109], v[108:109], 0, s[36:37]
	s_add_u32 m0, s101, 0x4800
	s_nop 0
	global_load_lds_dwordx4 v[110:111], off
	v_lshl_add_u64 v[110:111], v[110:111], 0, s[36:37]
	s_add_u32 m0, s101, 0x4c00
	s_nop 0
	global_load_lds_dwordx4 v[112:113], off
	v_lshl_add_u64 v[112:113], v[112:113], 0, s[36:37]
	s_mov_b32 s13, 1
.LgT4_p10_nopf:
	v_readlane_b32 s38, v248, 2
	v_readlane_b32 s39, v248, 3
	s_nop 3
	s_add_u32 s36, s38, 0x20000
	s_addc_u32 s37, s39, 0
	s_nop 7
	s_waitcnt vmcnt(63)
	v_fmac_f32_e32 v129, v50, v234
	global_store_dword v218, v129, s[38:39] nt
	s_waitcnt vmcnt(63)
	v_fmac_f32_e32 v130, v51, v234
	global_store_dword v219, v130, s[38:39] nt
	s_waitcnt vmcnt(63)
	v_fmac_f32_e32 v131, v52, v234
	global_store_dword v220, v131, s[38:39] nt
	s_waitcnt vmcnt(63)
	v_fmac_f32_e32 v132, v53, v234
	global_store_dword v221, v132, s[38:39] nt
	s_waitcnt vmcnt(63)
	v_fmac_f32_e32 v133, v54, v234
	global_store_dword v222, v133, s[38:39] nt
	s_waitcnt vmcnt(63)
	v_fmac_f32_e32 v134, v55, v234
	global_store_dword v223, v134, s[38:39] nt
	s_waitcnt vmcnt(63)
	v_fmac_f32_e32 v135, v56, v234
	global_store_dword v224, v135, s[38:39] nt
	s_waitcnt vmcnt(63)
	v_fmac_f32_e32 v136, v57, v234
	global_store_dword v225, v136, s[38:39] nt
	s_waitcnt vmcnt(63)
	v_fmac_f32_e32 v137, v58, v234
	global_store_dword v226, v137, s[38:39] nt
	s_waitcnt vmcnt(63)
	v_fmac_f32_e32 v138, v59, v234
	global_store_dword v227, v138, s[38:39] nt
	s_waitcnt vmcnt(63)
	v_fmac_f32_e32 v139, v60, v234
	global_store_dword v228, v139, s[38:39] nt
	s_waitcnt vmcnt(63)
	v_fmac_f32_e32 v140, v61, v234
	global_store_dword v229, v140, s[38:39] nt
	s_waitcnt vmcnt(63)
	v_fmac_f32_e32 v141, v62, v234
	global_store_dword v230, v141, s[38:39] nt
	s_waitcnt vmcnt(63)
	v_fmac_f32_e32 v142, v63, v234
	global_store_dword v231, v142, s[38:39] nt
	s_waitcnt vmcnt(63)
	v_fmac_f32_e32 v143, v64, v234
	global_store_dword v232, v143, s[38:39] nt
	s_waitcnt vmcnt(63)
	v_fmac_f32_e32 v144, v65, v234
	global_store_dword v233, v144, s[38:39] nt
	s_waitcnt vmcnt(63)
	v_fmac_f32_e32 v145, v34, v235
	global_store_dword v218, v145, s[38:39] offset:128 nt
	s_waitcnt vmcnt(63)
	v_fmac_f32_e32 v146, v35, v235
	global_store_dword v219, v146, s[38:39] offset:128 nt
	s_waitcnt vmcnt(63)
	v_fmac_f32_e32 v147, v36, v235
	global_store_dword v220, v147, s[38:39] offset:128 nt
	s_waitcnt vmcnt(63)
	v_fmac_f32_e32 v148, v37, v235
	global_store_dword v221, v148, s[38:39] offset:128 nt
	s_waitcnt vmcnt(63)
	v_fmac_f32_e32 v149, v38, v235
	global_store_dword v222, v149, s[38:39] offset:128 nt
	s_waitcnt vmcnt(63)
	v_fmac_f32_e32 v150, v39, v235
	global_store_dword v223, v150, s[38:39] offset:128 nt
	s_waitcnt vmcnt(63)
	v_fmac_f32_e32 v151, v40, v235
	global_store_dword v224, v151, s[38:39] offset:128 nt
	s_waitcnt vmcnt(63)
	v_fmac_f32_e32 v152, v41, v235
	global_store_dword v225, v152, s[38:39] offset:128 nt
	s_waitcnt vmcnt(63)
	v_fmac_f32_e32 v153, v42, v235
	global_store_dword v226, v153, s[38:39] offset:128 nt
	s_waitcnt vmcnt(63)
	v_fmac_f32_e32 v154, v43, v235
	global_store_dword v227, v154, s[38:39] offset:128 nt
	s_waitcnt vmcnt(63)
	v_fmac_f32_e32 v155, v44, v235
	global_store_dword v228, v155, s[38:39] offset:128 nt
	s_waitcnt vmcnt(63)
	v_fmac_f32_e32 v156, v45, v235
	global_store_dword v229, v156, s[38:39] offset:128 nt
	s_waitcnt vmcnt(63)
	v_fmac_f32_e32 v157, v46, v235
	global_store_dword v230, v157, s[38:39] offset:128 nt
	s_waitcnt vmcnt(63)
	v_fmac_f32_e32 v158, v47, v235
	global_store_dword v231, v158, s[38:39] offset:128 nt
	s_waitcnt vmcnt(63)
	v_fmac_f32_e32 v159, v48, v235
	global_store_dword v232, v159, s[38:39] offset:128 nt
	s_waitcnt vmcnt(63)
	v_fmac_f32_e32 v160, v49, v235
	global_store_dword v233, v160, s[38:39] offset:128 nt
	s_waitcnt vmcnt(63)
	v_fmac_f32_e32 v161, v18, v234
	global_store_dword v218, v161, s[36:37] nt
	s_waitcnt vmcnt(63)
	v_fmac_f32_e32 v162, v19, v234
	global_store_dword v219, v162, s[36:37] nt
	s_waitcnt vmcnt(63)
	v_fmac_f32_e32 v163, v20, v234
	global_store_dword v220, v163, s[36:37] nt
	s_waitcnt vmcnt(63)
	v_fmac_f32_e32 v164, v21, v234
	global_store_dword v221, v164, s[36:37] nt
	s_waitcnt vmcnt(63)
	v_fmac_f32_e32 v165, v22, v234
	global_store_dword v222, v165, s[36:37] nt
	s_waitcnt vmcnt(63)
	v_fmac_f32_e32 v166, v23, v234
	global_store_dword v223, v166, s[36:37] nt
	s_waitcnt vmcnt(63)
	v_fmac_f32_e32 v167, v24, v234
	global_store_dword v224, v167, s[36:37] nt
	s_waitcnt vmcnt(63)
	v_fmac_f32_e32 v168, v25, v234
	global_store_dword v225, v168, s[36:37] nt
	s_waitcnt vmcnt(63)
	v_fmac_f32_e32 v169, v26, v234
	global_store_dword v226, v169, s[36:37] nt
	s_waitcnt vmcnt(63)
	v_fmac_f32_e32 v170, v27, v234
	global_store_dword v227, v170, s[36:37] nt
	s_waitcnt vmcnt(63)
	v_fmac_f32_e32 v171, v28, v234
	global_store_dword v228, v171, s[36:37] nt
	s_waitcnt vmcnt(63)
	v_fmac_f32_e32 v172, v29, v234
	global_store_dword v229, v172, s[36:37] nt
	s_waitcnt vmcnt(63)
	v_fmac_f32_e32 v173, v30, v234
	global_store_dword v230, v173, s[36:37] nt
	s_waitcnt vmcnt(63)
	v_fmac_f32_e32 v174, v31, v234
	global_store_dword v231, v174, s[36:37] nt
	s_waitcnt vmcnt(63)
	v_fmac_f32_e32 v175, v32, v234
	global_store_dword v232, v175, s[36:37] nt
	s_waitcnt vmcnt(63)
	v_fmac_f32_e32 v176, v33, v234
	global_store_dword v233, v176, s[36:37] nt
	s_waitcnt vmcnt(63)
	v_fmac_f32_e32 v177, v2, v235
	global_store_dword v218, v177, s[36:37] offset:128 nt
	s_waitcnt vmcnt(63)
	v_fmac_f32_e32 v202, v3, v235
	global_store_dword v219, v202, s[36:37] offset:128 nt
	s_waitcnt vmcnt(63)
	v_fmac_f32_e32 v203, v4, v235
	global_store_dword v220, v203, s[36:37] offset:128 nt
	s_waitcnt vmcnt(63)
	v_fmac_f32_e32 v204, v5, v235
	global_store_dword v221, v204, s[36:37] offset:128 nt
	s_waitcnt vmcnt(63)
	v_fmac_f32_e32 v205, v6, v235
	global_store_dword v222, v205, s[36:37] offset:128 nt
	s_waitcnt vmcnt(63)
	v_fmac_f32_e32 v206, v7, v235
	global_store_dword v223, v206, s[36:37] offset:128 nt
	s_waitcnt vmcnt(63)
	v_fmac_f32_e32 v207, v8, v235
	global_store_dword v224, v207, s[36:37] offset:128 nt
	s_waitcnt vmcnt(63)
	v_fmac_f32_e32 v208, v9, v235
	global_store_dword v225, v208, s[36:37] offset:128 nt
	s_waitcnt vmcnt(63)
	v_fmac_f32_e32 v209, v10, v235
	global_store_dword v226, v209, s[36:37] offset:128 nt
	s_waitcnt vmcnt(63)
	v_fmac_f32_e32 v210, v11, v235
	global_store_dword v227, v210, s[36:37] offset:128 nt
	s_waitcnt vmcnt(63)
	v_fmac_f32_e32 v211, v12, v235
	global_store_dword v228, v211, s[36:37] offset:128 nt
	s_waitcnt vmcnt(63)
	v_fmac_f32_e32 v212, v13, v235
	global_store_dword v229, v212, s[36:37] offset:128 nt
	s_waitcnt vmcnt(63)
	v_fmac_f32_e32 v213, v14, v235
	global_store_dword v230, v213, s[36:37] offset:128 nt
	s_waitcnt vmcnt(63)
	v_fmac_f32_e32 v214, v15, v235
	global_store_dword v231, v214, s[36:37] offset:128 nt
	s_waitcnt vmcnt(63)
	v_fmac_f32_e32 v215, v16, v235
	global_store_dword v232, v215, s[36:37] offset:128 nt
	s_waitcnt vmcnt(63)
	v_fmac_f32_e32 v216, v17, v235
	global_store_dword v233, v216, s[36:37] offset:128 nt
	s_cmpk_gt_i32 s2, 0x13f
	s_cbranch_scc0 .LBB0_89

.LBB0_596:
.LBB0_597:
	v_readlane_b32 s0, v247, 62
	v_readlane_b32 s1, v247, 63
	s_andn2_b64 vcc, exec, s[0:1]
	s_cbranch_vccnz .LBB0_603
	v_readlane_b32 s2, v246, 46
	s_movk_i32 s4, 0x70
	s_mov_b32 s58, 0
.LBB0_599:
	s_ashr_i32 s0, s2, 31
	s_lshr_b32 s0, s0, 26
	s_add_i32 s0, s2, s0
	s_andn2_b32 s0, s0, 63
	s_sub_i32 s1, s2, s0
	s_bfe_i32 s22, s1, 0x80000
	s_bfe_u32 s22, s22, 0x3000c
	s_add_i32 s23, s1, s22
	s_bfe_i32 s22, s23, 0x80000
	s_sext_i32_i16 s22, s22
	s_and_b32 s22, s22, -8
	s_add_i32 s22, s22, s0
	v_readlane_b32 s0, v246, 0
	s_or_b32 s22, s22, s0
	s_and_b32 s0, s23, 0xf8
	s_sub_i32 s0, s1, s0
	s_sext_i32_i8 s0, s0
	s_lshl_b32 s23, s0, 7
	v_readlane_b32 s0, v246, 22
	s_lshl_b32 s24, s22, 7
	v_readlane_b32 s0, v245, 5
	v_readlane_b32 s1, v245, 6
	v_ashrrev_i32_e32 v1, 1, v184
	v_and_b32_e32 v1, 0xffffffc0, v1
	v_lshrrev_b32_e32 v67, 3, v184
	v_and_b32_e32 v67, 4, v67
	v_add_u32_e32 v1, s24, v1
	v_or_b32_e32 v1, v1, v67
	v_and_b32_e32 v68, 0x5f, v184
	v_or_b32_e32 v68, s23, v68
	v_lshlrev_b32_e32 v69, 2, v68
	v_lshl_add_u32 v70, v1, 12, v69
	s_add_i32 s28, s24, 0xffffe000
	s_ashr_i32 s28, s28, 12
	s_mulk_i32 s28, 0xc00
	s_addk_i32 s28, 0x800
	s_cmp_gt_i32 s22, 63
	s_cselect_b32 s28, s28, 0x6800
	v_add_lshl_u32 v71, v68, s28, 2
	v_mov_b32_e32 v218, v70
	v_add_u32_e32 v219, 0x1000, v70
	v_add_u32_e32 v220, 0x2000, v70
	v_add_u32_e32 v221, 0x3000, v70
	v_add_u32_e32 v222, 0x8000, v70
	v_add_u32_e32 v223, 0x9000, v70
	v_add_u32_e32 v224, 0xa000, v70
	v_add_u32_e32 v225, 0xb000, v70
	v_add_u32_e32 v226, 0x10000, v70
	v_add_u32_e32 v227, 0x11000, v70
	v_add_u32_e32 v228, 0x12000, v70
	v_add_u32_e32 v229, 0x13000, v70
	v_add_u32_e32 v230, 0x18000, v70
	v_add_u32_e32 v231, 0x19000, v70
	v_add_u32_e32 v232, 0x1a000, v70
	v_add_u32_e32 v233, 0x1b000, v70
	global_load_dword v234, v71, s[0:1]
	global_load_dword v235, v71, s[0:1] offset:128
	s_barrier
	v_lshrrev_b32_e32 v122, 6, v184
	v_and_b32_e32 v123, 63, v184
	v_readfirstlane_b32 s39, v122
	s_cmp_eq_u32 s58, 1
	s_cbranch_scc1 .LgT4_p5_skipptr
	v_lshrrev_b32_e32 v124, 4, v123
	v_and_b32_e32 v125, 15, v123
	v_lshlrev_b32_e32 v126, 2, v124
	v_xor_b32_e32 v125, v125, v126
	v_mul_u32_u24_e32 v124, 0x14000, v124
	v_readlane_b32 s0, v246, 22
	v_readlane_b32 s1, v246, 23
	s_nop 3
	s_lshl_b32 s101, s39, 12
	s_mul_i32 s100, s39, 0x140000
	s_lshl_b32 s28, s24, 1
	s_add_u32 s100, s100, s28
	s_add_u32 s100, s100, 0xb04a000
	s_add_u32 s28, s68, s100
	s_addc_u32 s29, s69, 0
	v_xor_b32_e32 v126, 0, v125
	v_lshl_add_u32 v126, v126, 4, v124
	v_mov_b32_e32 v127, 0
	v_lshl_add_u64 v[98:99], v[126:127], 0, s[28:29]
	s_add_u32 s28, s28, 0x50000
	s_addc_u32 s29, s29, 0
	v_xor_b32_e32 v126, 1, v125
	v_lshl_add_u32 v126, v126, 4, v124
	v_mov_b32_e32 v127, 0
	v_lshl_add_u64 v[100:101], v[126:127], 0, s[28:29]
	s_add_u32 s28, s28, 0x50000
	s_addc_u32 s29, s29, 0
	v_xor_b32_e32 v126, 2, v125
	v_lshl_add_u32 v126, v126, 4, v124
	v_mov_b32_e32 v127, 0
	v_lshl_add_u64 v[102:103], v[126:127], 0, s[28:29]
	s_add_u32 s28, s28, 0x50000
	s_addc_u32 s29, s29, 0
	v_xor_b32_e32 v126, 3, v125
	v_lshl_add_u32 v126, v126, 4, v124
	v_mov_b32_e32 v127, 0
	v_lshl_add_u64 v[104:105], v[126:127], 0, s[28:29]
	v_lshrrev_b32_e32 v124, 3, v123
	v_lshrrev_b32_e32 v125, 4, v123
	v_and_b32_e32 v126, 7, v123
	s_lshl_b32 s100, s39, 5
	s_add_i32 s100, s100, s23
	s_lshl_b32 s100, s100, 11
	s_add_u32 s0, s0, s100
	s_addc_u32 s1, s1, 0
	v_and_b32_e32 v127, 7, v125
	v_xor_b32_e32 v127, v126, v127
	v_lshlrev_b32_e32 v127, 4, v127
	v_lshl_add_u32 v128, v124, 11, v127
	v_mov_b32_e32 v96, v128
	v_mov_b32_e32 v97, 0
	v_lshl_add_u64 v[106:107], v[96:97], 0, s[0:1]
	s_add_u32 s0, s0, 0x4000
	s_addc_u32 s1, s1, 0
	v_add_u32_e32 v127, 4, v125
	v_and_b32_e32 v127, 7, v127
	v_xor_b32_e32 v127, v126, v127
	v_lshlrev_b32_e32 v127, 4, v127
	v_lshl_add_u32 v128, v124, 11, v127
	v_mov_b32_e32 v96, v128
	v_mov_b32_e32 v97, 0
	v_lshl_add_u64 v[108:109], v[96:97], 0, s[0:1]
	s_add_u32 s0, s0, 0x4000
	s_addc_u32 s1, s1, 0
	v_and_b32_e32 v127, 7, v125
	v_xor_b32_e32 v127, v126, v127
	v_lshlrev_b32_e32 v127, 4, v127
	v_lshl_add_u32 v128, v124, 11, v127
	v_mov_b32_e32 v96, v128
	v_mov_b32_e32 v97, 0
	v_lshl_add_u64 v[110:111], v[96:97], 0, s[0:1]
	s_add_u32 s0, s0, 0x4000
	s_addc_u32 s1, s1, 0
	v_add_u32_e32 v127, 4, v125
	v_and_b32_e32 v127, 7, v127
	v_xor_b32_e32 v127, v126, v127
	v_lshlrev_b32_e32 v127, 4, v127
	v_lshl_add_u32 v128, v124, 11, v127
	v_mov_b32_e32 v96, v128
	v_mov_b32_e32 v97, 0
	v_lshl_add_u64 v[112:113], v[96:97], 0, s[0:1]
	s_mov_b32 s28, 0x500000
	s_mov_b32 s29, 0
	s_mov_b32 s36, 128
	s_mov_b32 s37, 0
	s_add_u32 m0, s101, 0x0
	s_nop 0
	global_load_lds_dwordx4 v[98:99], off
	v_lshl_add_u64 v[98:99], v[98:99], 0, s[28:29]
	s_add_u32 m0, s101, 0x400
	s_nop 0
	global_load_lds_dwordx4 v[100:101], off
	v_lshl_add_u64 v[100:101], v[100:101], 0, s[28:29]
	s_add_u32 m0, s101, 0x800
	s_nop 0
	global_load_lds_dwordx4 v[102:103], off
	v_lshl_add_u64 v[102:103], v[102:103], 0, s[28:29]
	s_add_u32 m0, s101, 0xc00
	s_nop 0
	global_load_lds_dwordx4 v[104:105], off
	v_lshl_add_u64 v[104:105], v[104:105], 0, s[28:29]
	s_add_u32 m0, s101, 0x4000
	s_nop 0
	global_load_lds_dwordx4 v[106:107], off
	v_lshl_add_u64 v[106:107], v[106:107], 0, s[36:37]
	s_add_u32 m0, s101, 0x4400
	s_nop 0
	global_load_lds_dwordx4 v[108:109], off
	v_lshl_add_u64 v[108:109], v[108:109], 0, s[36:37]
	s_add_u32 m0, s101, 0x4800
	s_nop 0
	global_load_lds_dwordx4 v[110:111], off
	v_lshl_add_u64 v[110:111], v[110:111], 0, s[36:37]
	s_add_u32 m0, s101, 0x4c00
	s_nop 0
	global_load_lds_dwordx4 v[112:113], off
	v_lshl_add_u64 v[112:113], v[112:113], 0, s[36:37]
.LgT4_p5_skipptr:
	s_mov_b32 s28, 0x500000
	s_mov_b32 s29, 0
	s_mov_b32 s36, 128
	s_mov_b32 s37, 0
	v_and_b32_e32 v122, 31, v123
	v_lshrrev_b32_e32 v124, 5, v123
	v_bfe_u32 v125, v123, 4, 1
	v_bfe_u32 v126, v123, 2, 2
	v_and_b32_e32 v127, 3, v123
	s_lshr_b32 s38, s39, 1
	s_and_b32 s39, s39, 1
	v_lshlrev_b32_e32 v96, 1, v124
	v_add_u32_e32 v96, 0, v96
	v_and_b32_e32 v96, 3, v96
	v_lshl_or_b32 v96, v126, 2, v96
	v_lshrrev_b32_e32 v97, 1, v127
	v_lshl_or_b32 v97, v125, 1, v97
	v_or_b32_e32 v97, 0, v97
	s_lshl_b32 s0, s38, 3
	v_or_b32_e32 v97, s0, v97
	v_xor_b32_e32 v97, v97, v96
	v_lshlrev_b32_e32 v96, 3, v124
	v_add3_u32 v96, v96, v126, 0
	v_lshlrev_b32_e32 v96, 8, v96
	v_lshl_add_u32 v96, v97, 4, v96
	v_and_b32_e32 v97, 1, v127
	v_lshl_add_u32 v114, v97, 3, v96
	v_lshlrev_b32_e32 v96, 1, v124
	v_add_u32_e32 v96, 1, v96
	v_and_b32_e32 v96, 3, v96
	v_lshl_or_b32 v96, v126, 2, v96
	v_lshrrev_b32_e32 v97, 1, v127
	v_lshl_or_b32 v97, v125, 1, v97
	v_or_b32_e32 v97, 0, v97
	s_lshl_b32 s0, s38, 3
	v_or_b32_e32 v97, s0, v97
	v_xor_b32_e32 v97, v97, v96
	v_lshlrev_b32_e32 v96, 3, v124
	v_add3_u32 v96, v96, v126, 4
	v_lshlrev_b32_e32 v96, 8, v96
	v_lshl_add_u32 v96, v97, 4, v96
	v_and_b32_e32 v97, 1, v127
	v_lshl_add_u32 v115, v97, 3, v96
	v_lshlrev_b32_e32 v96, 1, v124
	v_add_u32_e32 v96, 0, v96
	v_and_b32_e32 v96, 3, v96
	v_lshl_or_b32 v96, v126, 2, v96
	v_lshrrev_b32_e32 v97, 1, v127
	v_lshl_or_b32 v97, v125, 1, v97
	v_or_b32_e32 v97, 4, v97
	s_lshl_b32 s0, s38, 3
	v_or_b32_e32 v97, s0, v97
	v_xor_b32_e32 v97, v97, v96
	v_lshlrev_b32_e32 v96, 3, v124
	v_add3_u32 v96, v96, v126, 0
	v_lshlrev_b32_e32 v96, 8, v96
	v_lshl_add_u32 v96, v97, 4, v96
	v_and_b32_e32 v97, 1, v127
	v_lshl_add_u32 v116, v97, 3, v96
	v_lshlrev_b32_e32 v96, 1, v124
	v_add_u32_e32 v96, 1, v96
	v_and_b32_e32 v96, 3, v96
	v_lshl_or_b32 v96, v126, 2, v96
	v_lshrrev_b32_e32 v97, 1, v127
	v_lshl_or_b32 v97, v125, 1, v97
	v_or_b32_e32 v97, 4, v97
	s_lshl_b32 s0, s38, 3
	v_or_b32_e32 v97, s0, v97
	v_xor_b32_e32 v97, v97, v96
	v_lshlrev_b32_e32 v96, 3, v124
	v_add3_u32 v96, v96, v126, 4
	v_lshlrev_b32_e32 v96, 8, v96
	v_lshl_add_u32 v96, v97, 4, v96
	v_and_b32_e32 v97, 1, v127
	v_lshl_add_u32 v117, v97, 3, v96
	v_bfe_u32 v96, v122, 1, 3
	v_xor_b32_e32 v96, v96, v124
	v_lshlrev_b32_e32 v96, 4, v96
	v_lshl_add_u32 v96, v122, 7, v96
	s_lshl_b32 s0, s39, 13
	v_add_u32_e32 v118, s0, v96
	v_xor_b32_e32 v119, 0x20, v118
	v_xor_b32_e32 v120, 0x40, v118
	v_xor_b32_e32 v121, 0x60, v118
	v_mov_b32_e32 v2, 0
	v_mov_b32_e32 v3, v2
	v_mov_b32_e32 v4, v2
	v_mov_b32_e32 v5, v2
	v_mov_b32_e32 v6, v2
	v_mov_b32_e32 v7, v2
	v_mov_b32_e32 v8, v2
	v_mov_b32_e32 v9, v2
	v_mov_b32_e32 v10, v2
	v_mov_b32_e32 v11, v2
	v_mov_b32_e32 v12, v2
	v_mov_b32_e32 v13, v2
	v_mov_b32_e32 v14, v2
	v_mov_b32_e32 v15, v2
	v_mov_b32_e32 v16, v2
	v_mov_b32_e32 v17, v2
	v_mov_b32_e32 v18, v2
	v_mov_b32_e32 v19, v2
	v_mov_b32_e32 v20, v2
	v_mov_b32_e32 v21, v2
	v_mov_b32_e32 v22, v2
	v_mov_b32_e32 v23, v2
	v_mov_b32_e32 v24, v2
	v_mov_b32_e32 v25, v2
	v_mov_b32_e32 v26, v2
	v_mov_b32_e32 v27, v2
	v_mov_b32_e32 v28, v2
	v_mov_b32_e32 v29, v2
	v_mov_b32_e32 v30, v2
	v_mov_b32_e32 v31, v2
	v_mov_b32_e32 v32, v2
	v_mov_b32_e32 v33, v2
	v_mov_b32_e32 v34, v2
	v_mov_b32_e32 v35, v2
	v_mov_b32_e32 v36, v2
	v_mov_b32_e32 v37, v2
	v_mov_b32_e32 v38, v2
	v_mov_b32_e32 v39, v2
	v_mov_b32_e32 v40, v2
	v_mov_b32_e32 v41, v2
	v_mov_b32_e32 v42, v2
	v_mov_b32_e32 v43, v2
	v_mov_b32_e32 v44, v2
	v_mov_b32_e32 v45, v2
	v_mov_b32_e32 v46, v2
	v_mov_b32_e32 v47, v2
	v_mov_b32_e32 v48, v2
	v_mov_b32_e32 v49, v2
	v_mov_b32_e32 v50, v2
	v_mov_b32_e32 v51, v2
	v_mov_b32_e32 v52, v2
	v_mov_b32_e32 v53, v2
	v_mov_b32_e32 v54, v2
	v_mov_b32_e32 v55, v2
	v_mov_b32_e32 v56, v2
	v_mov_b32_e32 v57, v2
	v_mov_b32_e32 v58, v2
	v_mov_b32_e32 v59, v2
	v_mov_b32_e32 v60, v2
	v_mov_b32_e32 v61, v2
	v_mov_b32_e32 v62, v2
	v_mov_b32_e32 v63, v2
	v_mov_b32_e32 v64, v2
	v_mov_b32_e32 v65, v2
	v_readlane_b32 s0, v248, 6
	v_readlane_b32 s1, v248, 7
	v_readlane_b32 s38, v248, 8
	v_readlane_b32 s39, v248, 9
	s_nop 3
	s_sub_u32 s38, s38, 0x2000000
	s_subb_u32 s39, s39, 0
	s_cmp_gt_i32 s22, 63
	s_cselect_b32 s0, s38, s0
	s_cselect_b32 s1, s39, s1
	s_add_u32 s38, s0, 0x20000
	s_addc_u32 s39, s1, 0
	s_mov_b32 s100, 7
.LgemmT_p5_loop:
	s_waitcnt vmcnt(0)
	s_barrier
	ds_read_b64_tr_b16 v[66:67], v114 offset:0
	ds_read_b64_tr_b16 v[68:69], v115 offset:0
	ds_read_b64_tr_b16 v[70:71], v116 offset:0
	ds_read_b64_tr_b16 v[72:73], v117 offset:0
	ds_read_b128 v[74:77], v118 offset:16384
	ds_read_b128 v[78:81], v118 offset:20480
	ds_read_b64_tr_b16 v[82:83], v114 offset:4096
	ds_read_b64_tr_b16 v[84:85], v115 offset:4096
	ds_read_b64_tr_b16 v[86:87], v116 offset:4096
	ds_read_b64_tr_b16 v[88:89], v117 offset:4096
	ds_read_b128 v[90:93], v119 offset:16384
	ds_read_b128 v[94:97], v119 offset:20480
	s_add_u32 m0, s101, 0x8000
	s_nop 0
	global_load_lds_dwordx4 v[98:99], off
	v_lshl_add_u64 v[98:99], v[98:99], 0, s[28:29]
	s_add_u32 m0, s101, 0x8400
	s_nop 0
	global_load_lds_dwordx4 v[100:101], off
	v_lshl_add_u64 v[100:101], v[100:101], 0, s[28:29]
	s_waitcnt lgkmcnt(6)
	v_mfma_f32_32x32x16_bf16 v[50:65], v[66:69], v[74:77], v[50:65]
	v_mfma_f32_32x32x16_bf16 v[34:49], v[66:69], v[78:81], v[34:49]
	v_mfma_f32_32x32x16_bf16 v[18:33], v[70:73], v[74:77], v[18:33]
	v_mfma_f32_32x32x16_bf16 v[2:17], v[70:73], v[78:81], v[2:17]
	ds_read_b64_tr_b16 v[66:67], v114 offset:8192
	ds_read_b64_tr_b16 v[68:69], v115 offset:8192
	ds_read_b64_tr_b16 v[70:71], v116 offset:8192
	ds_read_b64_tr_b16 v[72:73], v117 offset:8192
	ds_read_b128 v[74:77], v120 offset:16384
	ds_read_b128 v[78:81], v120 offset:20480
	s_add_u32 m0, s101, 0x8800
	s_nop 0
	global_load_lds_dwordx4 v[102:103], off
	v_lshl_add_u64 v[102:103], v[102:103], 0, s[28:29]
	s_add_u32 m0, s101, 0x8c00
	s_nop 0
	global_load_lds_dwordx4 v[104:105], off
	v_lshl_add_u64 v[104:105], v[104:105], 0, s[28:29]
	s_waitcnt lgkmcnt(6)
	v_mfma_f32_32x32x16_bf16 v[50:65], v[82:85], v[90:93], v[50:65]
	v_mfma_f32_32x32x16_bf16 v[34:49], v[82:85], v[94:97], v[34:49]
	v_mfma_f32_32x32x16_bf16 v[18:33], v[86:89], v[90:93], v[18:33]
	v_mfma_f32_32x32x16_bf16 v[2:17], v[86:89], v[94:97], v[2:17]
	ds_read_b64_tr_b16 v[82:83], v114 offset:12288
	ds_read_b64_tr_b16 v[84:85], v115 offset:12288
	ds_read_b64_tr_b16 v[86:87], v116 offset:12288
	ds_read_b64_tr_b16 v[88:89], v117 offset:12288
	ds_read_b128 v[90:93], v121 offset:16384
	ds_read_b128 v[94:97], v121 offset:20480
	s_add_u32 m0, s101, 0xc010
	s_nop 0
	global_load_lds_dwordx4 v[106:107], off
	v_lshl_add_u64 v[106:107], v[106:107], 0, s[36:37]
	s_add_u32 m0, s101, 0xc410
	s_nop 0
	global_load_lds_dwordx4 v[108:109], off
	v_lshl_add_u64 v[108:109], v[108:109], 0, s[36:37]
	s_waitcnt lgkmcnt(6)
	v_mfma_f32_32x32x16_bf16 v[50:65], v[66:69], v[74:77], v[50:65]
	v_mfma_f32_32x32x16_bf16 v[34:49], v[66:69], v[78:81], v[34:49]
	v_mfma_f32_32x32x16_bf16 v[18:33], v[70:73], v[74:77], v[18:33]
	v_mfma_f32_32x32x16_bf16 v[2:17], v[70:73], v[78:81], v[2:17]
	s_add_u32 m0, s101, 0xc810
	s_nop 0
	global_load_lds_dwordx4 v[110:111], off
	v_lshl_add_u64 v[110:111], v[110:111], 0, s[36:37]
	s_add_u32 m0, s101, 0xcc10
	s_nop 0
	global_load_lds_dwordx4 v[112:113], off
	v_lshl_add_u64 v[112:113], v[112:113], 0, s[36:37]
	s_waitcnt lgkmcnt(0)
	v_mfma_f32_32x32x16_bf16 v[50:65], v[82:85], v[90:93], v[50:65]
	v_mfma_f32_32x32x16_bf16 v[34:49], v[82:85], v[94:97], v[34:49]
	v_mfma_f32_32x32x16_bf16 v[18:33], v[86:89], v[90:93], v[18:33]
	v_mfma_f32_32x32x16_bf16 v[2:17], v[86:89], v[94:97], v[2:17]
	s_waitcnt vmcnt(0)
	s_barrier
	ds_read_b64_tr_b16 v[66:67], v114 offset:32768
	ds_read_b64_tr_b16 v[68:69], v115 offset:32768
	ds_read_b64_tr_b16 v[70:71], v116 offset:32768
	ds_read_b64_tr_b16 v[72:73], v117 offset:32768
	ds_read_b128 v[74:77], v118 offset:49168
	ds_read_b128 v[78:81], v118 offset:53264
	ds_read_b64_tr_b16 v[82:83], v114 offset:36864
	ds_read_b64_tr_b16 v[84:85], v115 offset:36864
	ds_read_b64_tr_b16 v[86:87], v116 offset:36864
	ds_read_b64_tr_b16 v[88:89], v117 offset:36864
	ds_read_b128 v[90:93], v119 offset:49168
	ds_read_b128 v[94:97], v119 offset:53264
	s_add_u32 m0, s101, 0x0
	s_nop 0
	global_load_lds_dwordx4 v[98:99], off
	v_lshl_add_u64 v[98:99], v[98:99], 0, s[28:29]
	s_add_u32 m0, s101, 0x400
	s_nop 0
	global_load_lds_dwordx4 v[100:101], off
	v_lshl_add_u64 v[100:101], v[100:101], 0, s[28:29]
	s_waitcnt lgkmcnt(6)
	v_mfma_f32_32x32x16_bf16 v[50:65], v[66:69], v[74:77], v[50:65]
	v_mfma_f32_32x32x16_bf16 v[34:49], v[66:69], v[78:81], v[34:49]
	v_mfma_f32_32x32x16_bf16 v[18:33], v[70:73], v[74:77], v[18:33]
	v_mfma_f32_32x32x16_bf16 v[2:17], v[70:73], v[78:81], v[2:17]
	ds_read_b64_tr_b16 v[66:67], v114 offset:40960
	ds_read_b64_tr_b16 v[68:69], v115 offset:40960
	ds_read_b64_tr_b16 v[70:71], v116 offset:40960
	ds_read_b64_tr_b16 v[72:73], v117 offset:40960
	ds_read_b128 v[74:77], v120 offset:49168
	ds_read_b128 v[78:81], v120 offset:53264
	s_add_u32 m0, s101, 0x800
	s_nop 0
	global_load_lds_dwordx4 v[102:103], off
	v_lshl_add_u64 v[102:103], v[102:103], 0, s[28:29]
	s_add_u32 m0, s101, 0xc00
	s_nop 0
	global_load_lds_dwordx4 v[104:105], off
	v_lshl_add_u64 v[104:105], v[104:105], 0, s[28:29]
	s_waitcnt lgkmcnt(6)
	v_mfma_f32_32x32x16_bf16 v[50:65], v[82:85], v[90:93], v[50:65]
	v_mfma_f32_32x32x16_bf16 v[34:49], v[82:85], v[94:97], v[34:49]
	v_mfma_f32_32x32x16_bf16 v[18:33], v[86:89], v[90:93], v[18:33]
	v_mfma_f32_32x32x16_bf16 v[2:17], v[86:89], v[94:97], v[2:17]
	ds_read_b64_tr_b16 v[82:83], v114 offset:45056
	ds_read_b64_tr_b16 v[84:85], v115 offset:45056
	ds_read_b64_tr_b16 v[86:87], v116 offset:45056
	ds_read_b64_tr_b16 v[88:89], v117 offset:45056
	ds_read_b128 v[90:93], v121 offset:49168
	ds_read_b128 v[94:97], v121 offset:53264
	s_add_u32 m0, s101, 0x4000
	s_nop 0
	global_load_lds_dwordx4 v[106:107], off
	v_lshl_add_u64 v[106:107], v[106:107], 0, s[36:37]
	s_add_u32 m0, s101, 0x4400
	s_nop 0
	global_load_lds_dwordx4 v[108:109], off
	v_lshl_add_u64 v[108:109], v[108:109], 0, s[36:37]
	s_waitcnt lgkmcnt(6)
	v_mfma_f32_32x32x16_bf16 v[50:65], v[66:69], v[74:77], v[50:65]
	v_mfma_f32_32x32x16_bf16 v[34:49], v[66:69], v[78:81], v[34:49]
	v_mfma_f32_32x32x16_bf16 v[18:33], v[70:73], v[74:77], v[18:33]
	v_mfma_f32_32x32x16_bf16 v[2:17], v[70:73], v[78:81], v[2:17]
	s_add_u32 m0, s101, 0x4800
	s_nop 0
	global_load_lds_dwordx4 v[110:111], off
	v_lshl_add_u64 v[110:111], v[110:111], 0, s[36:37]
	s_add_u32 m0, s101, 0x4c00
	s_nop 0
	global_load_lds_dwordx4 v[112:113], off
	v_lshl_add_u64 v[112:113], v[112:113], 0, s[36:37]
	s_waitcnt lgkmcnt(0)
	v_mfma_f32_32x32x16_bf16 v[50:65], v[82:85], v[90:93], v[50:65]
	v_mfma_f32_32x32x16_bf16 v[34:49], v[82:85], v[94:97], v[34:49]
	v_mfma_f32_32x32x16_bf16 v[18:33], v[86:89], v[90:93], v[18:33]
	v_mfma_f32_32x32x16_bf16 v[2:17], v[86:89], v[94:97], v[2:17]
	s_sub_u32 s100, s100, 1
	s_cmp_lg_u32 s100, 0
	s_cbranch_scc1 .LgemmT_p5_loop
	s_waitcnt vmcnt(0)
	s_barrier
	ds_read_b64_tr_b16 v[66:67], v114 offset:0
	ds_read_b64_tr_b16 v[68:69], v115 offset:0
	ds_read_b64_tr_b16 v[70:71], v116 offset:0
	ds_read_b64_tr_b16 v[72:73], v117 offset:0
	ds_read_b128 v[74:77], v118 offset:16384
	ds_read_b128 v[78:81], v118 offset:20480
	ds_read_b64_tr_b16 v[82:83], v114 offset:4096
	ds_read_b64_tr_b16 v[84:85], v115 offset:4096
	ds_read_b64_tr_b16 v[86:87], v116 offset:4096
	ds_read_b64_tr_b16 v[88:89], v117 offset:4096
	ds_read_b128 v[90:93], v119 offset:16384
	ds_read_b128 v[94:97], v119 offset:20480
	s_add_u32 m0, s101, 0x8000
	s_nop 0
	global_load_lds_dwordx4 v[98:99], off
	v_lshl_add_u64 v[98:99], v[98:99], 0, s[28:29]
	s_add_u32 m0, s101, 0x8400
	s_nop 0
	global_load_lds_dwordx4 v[100:101], off
	v_lshl_add_u64 v[100:101], v[100:101], 0, s[28:29]
	s_waitcnt lgkmcnt(6)
	v_mfma_f32_32x32x16_bf16 v[50:65], v[66:69], v[74:77], v[50:65]
	v_mfma_f32_32x32x16_bf16 v[34:49], v[66:69], v[78:81], v[34:49]
	v_mfma_f32_32x32x16_bf16 v[18:33], v[70:73], v[74:77], v[18:33]
	v_mfma_f32_32x32x16_bf16 v[2:17], v[70:73], v[78:81], v[2:17]
	ds_read_b64_tr_b16 v[66:67], v114 offset:8192
	ds_read_b64_tr_b16 v[68:69], v115 offset:8192
	ds_read_b64_tr_b16 v[70:71], v116 offset:8192
	ds_read_b64_tr_b16 v[72:73], v117 offset:8192
	ds_read_b128 v[74:77], v120 offset:16384
	ds_read_b128 v[78:81], v120 offset:20480
	s_add_u32 m0, s101, 0x8800
	s_nop 0
	global_load_lds_dwordx4 v[102:103], off
	v_lshl_add_u64 v[102:103], v[102:103], 0, s[28:29]
	s_add_u32 m0, s101, 0x8c00
	s_nop 0
	global_load_lds_dwordx4 v[104:105], off
	v_lshl_add_u64 v[104:105], v[104:105], 0, s[28:29]
	s_waitcnt lgkmcnt(6)
	v_mfma_f32_32x32x16_bf16 v[50:65], v[82:85], v[90:93], v[50:65]
	v_mfma_f32_32x32x16_bf16 v[34:49], v[82:85], v[94:97], v[34:49]
	v_mfma_f32_32x32x16_bf16 v[18:33], v[86:89], v[90:93], v[18:33]
	v_mfma_f32_32x32x16_bf16 v[2:17], v[86:89], v[94:97], v[2:17]
	ds_read_b64_tr_b16 v[82:83], v114 offset:12288
	ds_read_b64_tr_b16 v[84:85], v115 offset:12288
	ds_read_b64_tr_b16 v[86:87], v116 offset:12288
	ds_read_b64_tr_b16 v[88:89], v117 offset:12288
	ds_read_b128 v[90:93], v121 offset:16384
	ds_read_b128 v[94:97], v121 offset:20480
	s_add_u32 m0, s101, 0xc010
	s_nop 0
	global_load_lds_dwordx4 v[106:107], off
	v_lshl_add_u64 v[106:107], v[106:107], 0, s[36:37]
	s_add_u32 m0, s101, 0xc410
	s_nop 0
	global_load_lds_dwordx4 v[108:109], off
	v_lshl_add_u64 v[108:109], v[108:109], 0, s[36:37]
	s_waitcnt lgkmcnt(6)
	v_mfma_f32_32x32x16_bf16 v[50:65], v[66:69], v[74:77], v[50:65]
	v_mfma_f32_32x32x16_bf16 v[34:49], v[66:69], v[78:81], v[34:49]
	v_mfma_f32_32x32x16_bf16 v[18:33], v[70:73], v[74:77], v[18:33]
	v_mfma_f32_32x32x16_bf16 v[2:17], v[70:73], v[78:81], v[2:17]
	s_add_u32 m0, s101, 0xc810
	s_nop 0
	global_load_lds_dwordx4 v[110:111], off
	v_lshl_add_u64 v[110:111], v[110:111], 0, s[36:37]
	s_add_u32 m0, s101, 0xcc10
	s_nop 0
	global_load_lds_dwordx4 v[112:113], off
	v_lshl_add_u64 v[112:113], v[112:113], 0, s[36:37]
	s_waitcnt lgkmcnt(0)
	v_mfma_f32_32x32x16_bf16 v[50:65], v[82:85], v[90:93], v[50:65]
	v_mfma_f32_32x32x16_bf16 v[34:49], v[82:85], v[94:97], v[34:49]
	v_mfma_f32_32x32x16_bf16 v[18:33], v[86:89], v[90:93], v[18:33]
	v_mfma_f32_32x32x16_bf16 v[2:17], v[86:89], v[94:97], v[2:17]
	s_waitcnt vmcnt(0)
	s_barrier
	ds_read_b64_tr_b16 v[66:67], v114 offset:32768
	ds_read_b64_tr_b16 v[68:69], v115 offset:32768
	ds_read_b64_tr_b16 v[70:71], v116 offset:32768
	ds_read_b64_tr_b16 v[72:73], v117 offset:32768
	ds_read_b128 v[74:77], v118 offset:49168
	ds_read_b128 v[78:81], v118 offset:53264
	ds_read_b64_tr_b16 v[82:83], v114 offset:36864
	ds_read_b64_tr_b16 v[84:85], v115 offset:36864
	ds_read_b64_tr_b16 v[86:87], v116 offset:36864
	ds_read_b64_tr_b16 v[88:89], v117 offset:36864
	ds_read_b128 v[90:93], v119 offset:49168
	ds_read_b128 v[94:97], v119 offset:53264
	global_load_dword v129, v218, s[0:1] nt
	global_load_dword v130, v219, s[0:1] nt
	global_load_dword v131, v220, s[0:1] nt
	global_load_dword v132, v221, s[0:1] nt
	global_load_dword v133, v222, s[0:1] nt
	global_load_dword v134, v223, s[0:1] nt
	global_load_dword v135, v224, s[0:1] nt
	global_load_dword v136, v225, s[0:1] nt
	global_load_dword v137, v226, s[0:1] nt
	global_load_dword v138, v227, s[0:1] nt
	global_load_dword v139, v228, s[0:1] nt
	global_load_dword v140, v229, s[0:1] nt
	global_load_dword v141, v230, s[0:1] nt
	global_load_dword v142, v231, s[0:1] nt
	global_load_dword v143, v232, s[0:1] nt
	global_load_dword v144, v233, s[0:1] nt
	s_waitcnt lgkmcnt(6)
	v_mfma_f32_32x32x16_bf16 v[50:65], v[66:69], v[74:77], v[50:65]
	v_mfma_f32_32x32x16_bf16 v[34:49], v[66:69], v[78:81], v[34:49]
	v_mfma_f32_32x32x16_bf16 v[18:33], v[70:73], v[74:77], v[18:33]
	v_mfma_f32_32x32x16_bf16 v[2:17], v[70:73], v[78:81], v[2:17]
	ds_read_b64_tr_b16 v[66:67], v114 offset:40960
	ds_read_b64_tr_b16 v[68:69], v115 offset:40960
	ds_read_b64_tr_b16 v[70:71], v116 offset:40960
	ds_read_b64_tr_b16 v[72:73], v117 offset:40960
	ds_read_b128 v[74:77], v120 offset:49168
	ds_read_b128 v[78:81], v120 offset:53264
	global_load_dword v145, v218, s[0:1] offset:128 nt
	global_load_dword v146, v219, s[0:1] offset:128 nt
	global_load_dword v147, v220, s[0:1] offset:128 nt
	global_load_dword v148, v221, s[0:1] offset:128 nt
	global_load_dword v149, v222, s[0:1] offset:128 nt
	global_load_dword v150, v223, s[0:1] offset:128 nt
	global_load_dword v151, v224, s[0:1] offset:128 nt
	global_load_dword v152, v225, s[0:1] offset:128 nt
	global_load_dword v153, v226, s[0:1] offset:128 nt
	global_load_dword v154, v227, s[0:1] offset:128 nt
	global_load_dword v155, v228, s[0:1] offset:128 nt
	global_load_dword v156, v229, s[0:1] offset:128 nt
	global_load_dword v157, v230, s[0:1] offset:128 nt
	global_load_dword v158, v231, s[0:1] offset:128 nt
	global_load_dword v159, v232, s[0:1] offset:128 nt
	global_load_dword v160, v233, s[0:1] offset:128 nt
	s_waitcnt lgkmcnt(6)
	v_mfma_f32_32x32x16_bf16 v[50:65], v[82:85], v[90:93], v[50:65]
	v_mfma_f32_32x32x16_bf16 v[34:49], v[82:85], v[94:97], v[34:49]
	v_mfma_f32_32x32x16_bf16 v[18:33], v[86:89], v[90:93], v[18:33]
	v_mfma_f32_32x32x16_bf16 v[2:17], v[86:89], v[94:97], v[2:17]
	ds_read_b64_tr_b16 v[82:83], v114 offset:45056
	ds_read_b64_tr_b16 v[84:85], v115 offset:45056
	ds_read_b64_tr_b16 v[86:87], v116 offset:45056
	ds_read_b64_tr_b16 v[88:89], v117 offset:45056
	ds_read_b128 v[90:93], v121 offset:49168
	ds_read_b128 v[94:97], v121 offset:53264
	global_load_dword v161, v218, s[38:39] nt
	global_load_dword v162, v219, s[38:39] nt
	global_load_dword v163, v220, s[38:39] nt
	global_load_dword v164, v221, s[38:39] nt
	global_load_dword v165, v222, s[38:39] nt
	global_load_dword v166, v223, s[38:39] nt
	global_load_dword v167, v224, s[38:39] nt
	global_load_dword v168, v225, s[38:39] nt
	global_load_dword v169, v226, s[38:39] nt
	global_load_dword v170, v227, s[38:39] nt
	global_load_dword v171, v228, s[38:39] nt
	global_load_dword v172, v229, s[38:39] nt
	global_load_dword v173, v230, s[38:39] nt
	global_load_dword v174, v231, s[38:39] nt
	global_load_dword v175, v232, s[38:39] nt
	global_load_dword v176, v233, s[38:39] nt
	s_waitcnt lgkmcnt(6)
	v_mfma_f32_32x32x16_bf16 v[50:65], v[66:69], v[74:77], v[50:65]
	v_mfma_f32_32x32x16_bf16 v[34:49], v[66:69], v[78:81], v[34:49]
	v_mfma_f32_32x32x16_bf16 v[18:33], v[70:73], v[74:77], v[18:33]
	v_mfma_f32_32x32x16_bf16 v[2:17], v[70:73], v[78:81], v[2:17]
	global_load_dword v177, v218, s[38:39] offset:128 nt
	global_load_dword v202, v219, s[38:39] offset:128 nt
	global_load_dword v203, v220, s[38:39] offset:128 nt
	global_load_dword v204, v221, s[38:39] offset:128 nt
	global_load_dword v205, v222, s[38:39] offset:128 nt
	global_load_dword v206, v223, s[38:39] offset:128 nt
	global_load_dword v207, v224, s[38:39] offset:128 nt
	global_load_dword v208, v225, s[38:39] offset:128 nt
	global_load_dword v209, v226, s[38:39] offset:128 nt
	global_load_dword v210, v227, s[38:39] offset:128 nt
	global_load_dword v211, v228, s[38:39] offset:128 nt
	global_load_dword v212, v229, s[38:39] offset:128 nt
	global_load_dword v213, v230, s[38:39] offset:128 nt
	global_load_dword v214, v231, s[38:39] offset:128 nt
	global_load_dword v215, v232, s[38:39] offset:128 nt
	global_load_dword v216, v233, s[38:39] offset:128 nt
	s_waitcnt lgkmcnt(0)
	v_mfma_f32_32x32x16_bf16 v[50:65], v[82:85], v[90:93], v[50:65]
	v_mfma_f32_32x32x16_bf16 v[34:49], v[82:85], v[94:97], v[34:49]
	v_mfma_f32_32x32x16_bf16 v[18:33], v[86:89], v[90:93], v[18:33]
	v_mfma_f32_32x32x16_bf16 v[2:17], v[86:89], v[94:97], v[2:17]
	v_readlane_b32 s0, v246, 1
	s_nop 1
	s_add_i32 s2, s2, s0
	s_mov_b32 s58, 0
	s_cmpk_gt_i32 s2, 0x13f
	s_cbranch_scc1 .LgT4_p5_nopf
	s_ashr_i32 s0, s2, 31
	s_lshr_b32 s0, s0, 26
	s_add_i32 s0, s2, s0
	s_andn2_b32 s0, s0, 63
	s_sub_i32 s1, s2, s0
	s_bfe_i32 s22, s1, 0x80000
	s_bfe_u32 s22, s22, 0x3000c
	s_add_i32 s23, s1, s22
	s_bfe_i32 s22, s23, 0x80000
	s_sext_i32_i16 s22, s22
	s_and_b32 s22, s22, -8
	s_add_i32 s22, s22, s0
	v_readlane_b32 s0, v246, 0
	s_or_b32 s22, s22, s0
	s_and_b32 s0, s23, 0xf8
	s_sub_i32 s0, s1, s0
	s_sext_i32_i8 s0, s0
	s_lshl_b32 s23, s0, 7
	v_readlane_b32 s0, v246, 22
	s_lshl_b32 s24, s22, 7
	v_lshrrev_b32_e32 v122, 6, v184
	v_and_b32_e32 v123, 63, v184
	v_readfirstlane_b32 s39, v122
	v_lshrrev_b32_e32 v124, 4, v123
	v_and_b32_e32 v125, 15, v123
	v_lshlrev_b32_e32 v126, 2, v124
	v_xor_b32_e32 v125, v125, v126
	v_mul_u32_u24_e32 v124, 0x14000, v124
	v_readlane_b32 s0, v246, 22
	v_readlane_b32 s1, v246, 23
	s_nop 3
	s_lshl_b32 s101, s39, 12
	s_mul_i32 s100, s39, 0x140000
	s_lshl_b32 s28, s24, 1
	s_add_u32 s100, s100, s28
	s_add_u32 s100, s100, 0xb04a000
	s_add_u32 s28, s68, s100
	s_addc_u32 s29, s69, 0
	v_xor_b32_e32 v126, 0, v125
	v_lshl_add_u32 v126, v126, 4, v124
	v_mov_b32_e32 v127, 0
	v_lshl_add_u64 v[98:99], v[126:127], 0, s[28:29]
	s_add_u32 s28, s28, 0x50000
	s_addc_u32 s29, s29, 0
	v_xor_b32_e32 v126, 1, v125
	v_lshl_add_u32 v126, v126, 4, v124
	v_mov_b32_e32 v127, 0
	v_lshl_add_u64 v[100:101], v[126:127], 0, s[28:29]
	s_add_u32 s28, s28, 0x50000
	s_addc_u32 s29, s29, 0
	v_xor_b32_e32 v126, 2, v125
	v_lshl_add_u32 v126, v126, 4, v124
	v_mov_b32_e32 v127, 0
	v_lshl_add_u64 v[102:103], v[126:127], 0, s[28:29]
	s_add_u32 s28, s28, 0x50000
	s_addc_u32 s29, s29, 0
	v_xor_b32_e32 v126, 3, v125
	v_lshl_add_u32 v126, v126, 4, v124
	v_mov_b32_e32 v127, 0
	v_lshl_add_u64 v[104:105], v[126:127], 0, s[28:29]
	v_lshrrev_b32_e32 v124, 3, v123
	v_lshrrev_b32_e32 v125, 4, v123
	v_and_b32_e32 v126, 7, v123
	s_lshl_b32 s100, s39, 5
	s_add_i32 s100, s100, s23
	s_lshl_b32 s100, s100, 11
	s_add_u32 s0, s0, s100
	s_addc_u32 s1, s1, 0
	v_and_b32_e32 v127, 7, v125
	v_xor_b32_e32 v127, v126, v127
	v_lshlrev_b32_e32 v127, 4, v127
	v_lshl_add_u32 v128, v124, 11, v127
	v_mov_b32_e32 v96, v128
	v_mov_b32_e32 v97, 0
	v_lshl_add_u64 v[106:107], v[96:97], 0, s[0:1]
	s_add_u32 s0, s0, 0x4000
	s_addc_u32 s1, s1, 0
	v_add_u32_e32 v127, 4, v125
	v_and_b32_e32 v127, 7, v127
	v_xor_b32_e32 v127, v126, v127
	v_lshlrev_b32_e32 v127, 4, v127
	v_lshl_add_u32 v128, v124, 11, v127
	v_mov_b32_e32 v96, v128
	v_mov_b32_e32 v97, 0
	v_lshl_add_u64 v[108:109], v[96:97], 0, s[0:1]
	s_add_u32 s0, s0, 0x4000
	s_addc_u32 s1, s1, 0
	v_and_b32_e32 v127, 7, v125
	v_xor_b32_e32 v127, v126, v127
	v_lshlrev_b32_e32 v127, 4, v127
	v_lshl_add_u32 v128, v124, 11, v127
	v_mov_b32_e32 v96, v128
	v_mov_b32_e32 v97, 0
	v_lshl_add_u64 v[110:111], v[96:97], 0, s[0:1]
	s_add_u32 s0, s0, 0x4000
	s_addc_u32 s1, s1, 0
	v_add_u32_e32 v127, 4, v125
	v_and_b32_e32 v127, 7, v127
	v_xor_b32_e32 v127, v126, v127
	v_lshlrev_b32_e32 v127, 4, v127
	v_lshl_add_u32 v128, v124, 11, v127
	v_mov_b32_e32 v96, v128
	v_mov_b32_e32 v97, 0
	v_lshl_add_u64 v[112:113], v[96:97], 0, s[0:1]
	s_mov_b32 s28, 0x500000
	s_mov_b32 s29, 0
	s_mov_b32 s36, 128
	s_mov_b32 s37, 0
	s_add_u32 m0, s101, 0x0
	s_nop 0
	global_load_lds_dwordx4 v[98:99], off
	v_lshl_add_u64 v[98:99], v[98:99], 0, s[28:29]
	s_add_u32 m0, s101, 0x400
	s_nop 0
	global_load_lds_dwordx4 v[100:101], off
	v_lshl_add_u64 v[100:101], v[100:101], 0, s[28:29]
	s_add_u32 m0, s101, 0x800
	s_nop 0
	global_load_lds_dwordx4 v[102:103], off
	v_lshl_add_u64 v[102:103], v[102:103], 0, s[28:29]
	s_add_u32 m0, s101, 0xc00
	s_nop 0
	global_load_lds_dwordx4 v[104:105], off
	v_lshl_add_u64 v[104:105], v[104:105], 0, s[28:29]
	s_add_u32 m0, s101, 0x4000
	s_nop 0
	global_load_lds_dwordx4 v[106:107], off
	v_lshl_add_u64 v[106:107], v[106:107], 0, s[36:37]
	s_add_u32 m0, s101, 0x4400
	s_nop 0
	global_load_lds_dwordx4 v[108:109], off
	v_lshl_add_u64 v[108:109], v[108:109], 0, s[36:37]
	s_add_u32 m0, s101, 0x4800
	s_nop 0
	global_load_lds_dwordx4 v[110:111], off
	v_lshl_add_u64 v[110:111], v[110:111], 0, s[36:37]
	s_add_u32 m0, s101, 0x4c00
	s_nop 0
	global_load_lds_dwordx4 v[112:113], off
	v_lshl_add_u64 v[112:113], v[112:113], 0, s[36:37]
	s_mov_b32 s58, 1
.LgT4_p5_nopf:
	v_readlane_b32 s38, v248, 2
	v_readlane_b32 s39, v248, 3
	s_nop 3
	s_add_u32 s36, s38, 0x20000
	s_addc_u32 s37, s39, 0
	s_nop 7
	s_waitcnt vmcnt(63)
	v_fmac_f32_e32 v129, v50, v234
	global_store_dword v218, v129, s[38:39]
	s_waitcnt vmcnt(63)
	v_fmac_f32_e32 v130, v51, v234
	global_store_dword v219, v130, s[38:39]
	s_waitcnt vmcnt(63)
	v_fmac_f32_e32 v131, v52, v234
	global_store_dword v220, v131, s[38:39]
	s_waitcnt vmcnt(63)
	v_fmac_f32_e32 v132, v53, v234
	global_store_dword v221, v132, s[38:39]
	s_waitcnt vmcnt(63)
	v_fmac_f32_e32 v133, v54, v234
	global_store_dword v222, v133, s[38:39]
	s_waitcnt vmcnt(63)
	v_fmac_f32_e32 v134, v55, v234
	global_store_dword v223, v134, s[38:39]
	s_waitcnt vmcnt(63)
	v_fmac_f32_e32 v135, v56, v234
	global_store_dword v224, v135, s[38:39]
	s_waitcnt vmcnt(63)
	v_fmac_f32_e32 v136, v57, v234
	global_store_dword v225, v136, s[38:39]
	s_waitcnt vmcnt(63)
	v_fmac_f32_e32 v137, v58, v234
	global_store_dword v226, v137, s[38:39]
	s_waitcnt vmcnt(63)
	v_fmac_f32_e32 v138, v59, v234
	global_store_dword v227, v138, s[38:39]
	s_waitcnt vmcnt(63)
	v_fmac_f32_e32 v139, v60, v234
	global_store_dword v228, v139, s[38:39]
	s_waitcnt vmcnt(63)
	v_fmac_f32_e32 v140, v61, v234
	global_store_dword v229, v140, s[38:39]
	s_waitcnt vmcnt(63)
	v_fmac_f32_e32 v141, v62, v234
	global_store_dword v230, v141, s[38:39]
	s_waitcnt vmcnt(63)
	v_fmac_f32_e32 v142, v63, v234
	global_store_dword v231, v142, s[38:39]
	s_waitcnt vmcnt(63)
	v_fmac_f32_e32 v143, v64, v234
	global_store_dword v232, v143, s[38:39]
	s_waitcnt vmcnt(63)
	v_fmac_f32_e32 v144, v65, v234
	global_store_dword v233, v144, s[38:39]
	s_waitcnt vmcnt(63)
	v_fmac_f32_e32 v145, v34, v235
	global_store_dword v218, v145, s[38:39] offset:128
	s_waitcnt vmcnt(63)
	v_fmac_f32_e32 v146, v35, v235
	global_store_dword v219, v146, s[38:39] offset:128
	s_waitcnt vmcnt(63)
	v_fmac_f32_e32 v147, v36, v235
	global_store_dword v220, v147, s[38:39] offset:128
	s_waitcnt vmcnt(63)
	v_fmac_f32_e32 v148, v37, v235
	global_store_dword v221, v148, s[38:39] offset:128
	s_waitcnt vmcnt(63)
	v_fmac_f32_e32 v149, v38, v235
	global_store_dword v222, v149, s[38:39] offset:128
	s_waitcnt vmcnt(63)
	v_fmac_f32_e32 v150, v39, v235
	global_store_dword v223, v150, s[38:39] offset:128
	s_waitcnt vmcnt(63)
	v_fmac_f32_e32 v151, v40, v235
	global_store_dword v224, v151, s[38:39] offset:128
	s_waitcnt vmcnt(63)
	v_fmac_f32_e32 v152, v41, v235
	global_store_dword v225, v152, s[38:39] offset:128
	s_waitcnt vmcnt(63)
	v_fmac_f32_e32 v153, v42, v235
	global_store_dword v226, v153, s[38:39] offset:128
	s_waitcnt vmcnt(63)
	v_fmac_f32_e32 v154, v43, v235
	global_store_dword v227, v154, s[38:39] offset:128
	s_waitcnt vmcnt(63)
	v_fmac_f32_e32 v155, v44, v235
	global_store_dword v228, v155, s[38:39] offset:128
	s_waitcnt vmcnt(63)
	v_fmac_f32_e32 v156, v45, v235
	global_store_dword v229, v156, s[38:39] offset:128
	s_waitcnt vmcnt(63)
	v_fmac_f32_e32 v157, v46, v235
	global_store_dword v230, v157, s[38:39] offset:128
	s_waitcnt vmcnt(63)
	v_fmac_f32_e32 v158, v47, v235
	global_store_dword v231, v158, s[38:39] offset:128
	s_waitcnt vmcnt(63)
	v_fmac_f32_e32 v159, v48, v235
	global_store_dword v232, v159, s[38:39] offset:128
	s_waitcnt vmcnt(63)
	v_fmac_f32_e32 v160, v49, v235
	global_store_dword v233, v160, s[38:39] offset:128
	s_waitcnt vmcnt(63)
	v_fmac_f32_e32 v161, v18, v234
	global_store_dword v218, v161, s[36:37]
	s_waitcnt vmcnt(63)
	v_fmac_f32_e32 v162, v19, v234
	global_store_dword v219, v162, s[36:37]
	s_waitcnt vmcnt(63)
	v_fmac_f32_e32 v163, v20, v234
	global_store_dword v220, v163, s[36:37]
	s_waitcnt vmcnt(63)
	v_fmac_f32_e32 v164, v21, v234
	global_store_dword v221, v164, s[36:37]
	s_waitcnt vmcnt(63)
	v_fmac_f32_e32 v165, v22, v234
	global_store_dword v222, v165, s[36:37]
	s_waitcnt vmcnt(63)
	v_fmac_f32_e32 v166, v23, v234
	global_store_dword v223, v166, s[36:37]
	s_waitcnt vmcnt(63)
	v_fmac_f32_e32 v167, v24, v234
	global_store_dword v224, v167, s[36:37]
	s_waitcnt vmcnt(63)
	v_fmac_f32_e32 v168, v25, v234
	global_store_dword v225, v168, s[36:37]
	s_waitcnt vmcnt(63)
	v_fmac_f32_e32 v169, v26, v234
	global_store_dword v226, v169, s[36:37]
	s_waitcnt vmcnt(63)
	v_fmac_f32_e32 v170, v27, v234
	global_store_dword v227, v170, s[36:37]
	s_waitcnt vmcnt(63)
	v_fmac_f32_e32 v171, v28, v234
	global_store_dword v228, v171, s[36:37]
	s_waitcnt vmcnt(63)
	v_fmac_f32_e32 v172, v29, v234
	global_store_dword v229, v172, s[36:37]
	s_waitcnt vmcnt(63)
	v_fmac_f32_e32 v173, v30, v234
	global_store_dword v230, v173, s[36:37]
	s_waitcnt vmcnt(63)
	v_fmac_f32_e32 v174, v31, v234
	global_store_dword v231, v174, s[36:37]
	s_waitcnt vmcnt(63)
	v_fmac_f32_e32 v175, v32, v234
	global_store_dword v232, v175, s[36:37]
	s_waitcnt vmcnt(63)
	v_fmac_f32_e32 v176, v33, v234
	global_store_dword v233, v176, s[36:37]
	s_waitcnt vmcnt(63)
	v_fmac_f32_e32 v177, v2, v235
	global_store_dword v218, v177, s[36:37] offset:128
	s_waitcnt vmcnt(63)
	v_fmac_f32_e32 v202, v3, v235
	global_store_dword v219, v202, s[36:37] offset:128
	s_waitcnt vmcnt(63)
	v_fmac_f32_e32 v203, v4, v235
	global_store_dword v220, v203, s[36:37] offset:128
	s_waitcnt vmcnt(63)
	v_fmac_f32_e32 v204, v5, v235
	global_store_dword v221, v204, s[36:37] offset:128
	s_waitcnt vmcnt(63)
	v_fmac_f32_e32 v205, v6, v235
	global_store_dword v222, v205, s[36:37] offset:128
	s_waitcnt vmcnt(63)
	v_fmac_f32_e32 v206, v7, v235
	global_store_dword v223, v206, s[36:37] offset:128
	s_waitcnt vmcnt(63)
	v_fmac_f32_e32 v207, v8, v235
	global_store_dword v224, v207, s[36:37] offset:128
	s_waitcnt vmcnt(63)
	v_fmac_f32_e32 v208, v9, v235
	global_store_dword v225, v208, s[36:37] offset:128
	s_waitcnt vmcnt(63)
	v_fmac_f32_e32 v209, v10, v235
	global_store_dword v226, v209, s[36:37] offset:128
	s_waitcnt vmcnt(63)
	v_fmac_f32_e32 v210, v11, v235
	global_store_dword v227, v210, s[36:37] offset:128
	s_waitcnt vmcnt(63)
	v_fmac_f32_e32 v211, v12, v235
	global_store_dword v228, v211, s[36:37] offset:128
	s_waitcnt vmcnt(63)
	v_fmac_f32_e32 v212, v13, v235
	global_store_dword v229, v212, s[36:37] offset:128
	s_waitcnt vmcnt(63)
	v_fmac_f32_e32 v213, v14, v235
	global_store_dword v230, v213, s[36:37] offset:128
	s_waitcnt vmcnt(63)
	v_fmac_f32_e32 v214, v15, v235
	global_store_dword v231, v214, s[36:37] offset:128
	s_waitcnt vmcnt(63)
	v_fmac_f32_e32 v215, v16, v235
	global_store_dword v232, v215, s[36:37] offset:128
	s_waitcnt vmcnt(63)
	v_fmac_f32_e32 v216, v17, v235
	global_store_dword v233, v216, s[36:37] offset:128
	s_cmpk_gt_i32 s2, 0x13f
	s_cbranch_scc0 .LBB0_599
	v_readlane_b32 s52, v245, 56
	v_readlane_b32 s54, v245, 58
	v_readlane_b32 s55, v245, 59
	v_readlane_b32 s56, v245, 60
	v_readlane_b32 s57, v245, 61
	v_readlane_b32 s58, v245, 62
	v_readlane_b32 s59, v245, 63
	v_readlane_b32 s60, v244, 0
	v_readlane_b32 s61, v244, 1
	v_readlane_b32 s62, v244, 2
	v_readlane_b32 s63, v244, 3
	v_readlane_b32 s64, v244, 4
	v_readlane_b32 s65, v244, 5
	v_readlane_b32 s66, v244, 6
	v_readlane_b32 s67, v244, 7
	s_movk_i32 s43, 0x1fff
	v_readlane_b32 s53, v245, 57
